# v26 + nt on single-use f32 weight reads (transposing prologue) and on the last read of the residual stream in the final norm
# baseline (speedup 1.0000x reference)
; #pragma unroll 8
;     for (int i = 0; i < 32; ++i) { const int kk = 2 * i + (lane >> 5); scr[kk * 33 + (lane & 31)] = W[(size_t)(k0 + kk) * N + n0 + (lane & 31)]; }
.LBB0_18:
	s_lshl_b32 s11, s7, 1
	s_lshl_b32 s14, s9, 1
	v_or_b32_e32 v6, s11, v1
	v_or_b32_e32 v39, s14, v2
	s_add_i32 s15, s11, 4
	s_add_i32 s16, s14, 4
	s_add_i32 s17, s11, 8
	s_add_i32 s20, s14, 8
	s_add_i32 s21, s11, 12
	s_add_i32 s24, s14, 12
	s_add_i32 s25, s11, 16
	s_add_i32 s26, s14, 16
	s_add_i32 s27, s11, 20
	s_add_i32 s28, s14, 20
	s_add_i32 s29, s11, 24
	s_add_i32 s30, s14, 24
	s_add_i32 s11, s11, 28
	s_add_i32 s14, s14, 28
	v_add_u32_e32 v40, s6, v39
	v_or_b32_e32 v70, s15, v1
	v_or_b32_e32 v71, s16, v2
	v_or_b32_e32 v72, s17, v1
	v_or_b32_e32 v73, s20, v2
	v_or_b32_e32 v74, s21, v1
	v_or_b32_e32 v75, s24, v2
	v_or_b32_e32 v76, s25, v1
	v_or_b32_e32 v77, s26, v2
	v_or_b32_e32 v78, s27, v1
	v_or_b32_e32 v79, s28, v2
	v_or_b32_e32 v80, s29, v1
	v_or_b32_e32 v81, s30, v2
	v_or_b32_e32 v82, s11, v1
	v_or_b32_e32 v83, s14, v2
	v_add_u32_e32 v34, s0, v6
	v_ashrrev_i32_e32 v41, 31, v40
	v_add_u32_e32 v42, s0, v70
	v_add_u32_e32 v44, s6, v71
	v_add_u32_e32 v46, s0, v72
	v_add_u32_e32 v48, s6, v73
	v_add_u32_e32 v50, s0, v74
	v_add_u32_e32 v52, s6, v75
	v_add_u32_e32 v54, s0, v76
	v_add_u32_e32 v56, s6, v77
	v_add_u32_e32 v58, s0, v78
	v_add_u32_e32 v60, s6, v79
	v_add_u32_e32 v62, s0, v80
	v_add_u32_e32 v64, s6, v81
	v_add_u32_e32 v66, s0, v82
	v_add_u32_e32 v68, s6, v83
	v_ashrrev_i32_e32 v35, 31, v34
	v_lshlrev_b64 v[40:41], 11, v[40:41]
	v_ashrrev_i32_e32 v45, 31, v44
	v_ashrrev_i32_e32 v43, 31, v42
	v_ashrrev_i32_e32 v49, 31, v48
	v_ashrrev_i32_e32 v47, 31, v46
	v_ashrrev_i32_e32 v53, 31, v52
	v_ashrrev_i32_e32 v51, 31, v50
	v_ashrrev_i32_e32 v57, 31, v56
	v_ashrrev_i32_e32 v55, 31, v54
	v_ashrrev_i32_e32 v61, 31, v60
	v_ashrrev_i32_e32 v59, 31, v58
	v_ashrrev_i32_e32 v65, 31, v64
	v_ashrrev_i32_e32 v63, 31, v62
	v_ashrrev_i32_e32 v69, 31, v68
	v_ashrrev_i32_e32 v67, 31, v66
	v_lshlrev_b64 v[34:35], 11, v[34:35]
	v_lshl_add_u64 v[40:41], v[32:33], 0, v[40:41]
	v_lshlrev_b64 v[42:43], 11, v[42:43]
	v_lshlrev_b64 v[44:45], 11, v[44:45]
	v_lshlrev_b64 v[46:47], 11, v[46:47]
	v_lshlrev_b64 v[48:49], 11, v[48:49]
	v_lshlrev_b64 v[50:51], 11, v[50:51]
	v_lshlrev_b64 v[52:53], 11, v[52:53]
	v_lshlrev_b64 v[54:55], 11, v[54:55]
	v_lshlrev_b64 v[56:57], 11, v[56:57]
	v_lshlrev_b64 v[58:59], 11, v[58:59]
	v_lshlrev_b64 v[60:61], 11, v[60:61]
	v_lshlrev_b64 v[62:63], 11, v[62:63]
	v_lshlrev_b64 v[64:65], 11, v[64:65]
	v_lshlrev_b64 v[66:67], 11, v[66:67]
	v_lshlrev_b64 v[68:69], 11, v[68:69]
	v_lshl_add_u64 v[34:35], v[32:33], 0, v[34:35]
	v_lshl_add_u64 v[44:45], v[32:33], 0, v[44:45]
	v_lshl_add_u64 v[42:43], v[32:33], 0, v[42:43]
	v_lshl_add_u64 v[48:49], v[32:33], 0, v[48:49]
	v_lshl_add_u64 v[46:47], v[32:33], 0, v[46:47]
	v_lshl_add_u64 v[52:53], v[32:33], 0, v[52:53]
	v_lshl_add_u64 v[50:51], v[32:33], 0, v[50:51]
	v_lshl_add_u64 v[56:57], v[32:33], 0, v[56:57]
	v_lshl_add_u64 v[54:55], v[32:33], 0, v[54:55]
	v_lshl_add_u64 v[60:61], v[32:33], 0, v[60:61]
	v_lshl_add_u64 v[58:59], v[32:33], 0, v[58:59]
	v_lshl_add_u64 v[64:65], v[32:33], 0, v[64:65]
	v_lshl_add_u64 v[62:63], v[32:33], 0, v[62:63]
	v_lshl_add_u64 v[68:69], v[32:33], 0, v[68:69]
	v_lshl_add_u64 v[66:67], v[32:33], 0, v[66:67]
	global_load_dword v84, v[40:41], off nt
	global_load_dword v85, v[34:35], off nt
	global_load_dword v86, v[44:45], off nt
	global_load_dword v87, v[42:43], off nt
	global_load_dword v88, v[48:49], off nt
	global_load_dword v89, v[46:47], off nt
	global_load_dword v90, v[52:53], off nt
	global_load_dword v91, v[50:51], off nt
	global_load_dword v92, v[56:57], off nt
	global_load_dword v93, v[54:55], off nt
	global_load_dword v94, v[60:61], off nt
	global_load_dword v95, v[58:59], off nt
	global_load_dword v96, v[64:65], off nt
	global_load_dword v97, v[62:63], off nt
	global_load_dword v98, v[68:69], off nt
	global_load_dword v99, v[66:67], off nt
	s_add_i32 s9, s9, 16
	s_add_i32 s7, s7, 16
	s_add_i32 s10, s10, -16
	v_mad_u64_u32 v[34:35], s[14:15], v39, s3, v[8:9]
	s_cmp_lg_u32 s10, 0
	v_mad_u64_u32 v[40:41], s[14:15], v6, s3, v[8:9]
	v_mad_u64_u32 v[42:43], s[14:15], v71, s3, v[8:9]
	v_mad_u64_u32 v[44:45], s[14:15], v70, s3, v[8:9]
	v_mad_u64_u32 v[46:47], s[14:15], v73, s3, v[8:9]
	v_mad_u64_u32 v[48:49], s[14:15], v72, s3, v[8:9]
	v_mad_u64_u32 v[50:51], s[14:15], v75, s3, v[8:9]
	v_mad_u64_u32 v[52:53], s[14:15], v74, s3, v[8:9]
	v_mad_u64_u32 v[54:55], s[14:15], v77, s3, v[8:9]
	v_mad_u64_u32 v[56:57], s[14:15], v76, s3, v[8:9]
	v_mad_u64_u32 v[58:59], s[14:15], v79, s3, v[8:9]
	v_mad_u64_u32 v[60:61], s[14:15], v78, s3, v[8:9]
	v_mad_u64_u32 v[62:63], s[14:15], v81, s3, v[8:9]
	v_mad_u64_u32 v[64:65], s[14:15], v80, s3, v[8:9]
	v_mad_u64_u32 v[66:67], s[14:15], v83, s3, v[8:9]
	v_mad_u64_u32 v[68:69], s[14:15], v82, s3, v[8:9]
	s_waitcnt vmcnt(15)
	ds_write_b32 v34, v84
	s_waitcnt vmcnt(14)
	ds_write_b32 v40, v85
	s_waitcnt vmcnt(13)
	ds_write_b32 v42, v86
	s_waitcnt vmcnt(12)
	ds_write_b32 v44, v87
	s_waitcnt vmcnt(11)
	ds_write_b32 v46, v88
	s_waitcnt vmcnt(10)
	ds_write_b32 v48, v89
	s_waitcnt vmcnt(9)
	ds_write_b32 v50, v90
	s_waitcnt vmcnt(8)
	ds_write_b32 v52, v91
	s_waitcnt vmcnt(7)
	ds_write_b32 v54, v92
	s_waitcnt vmcnt(6)
	ds_write_b32 v56, v93
	s_waitcnt vmcnt(5)
	ds_write_b32 v58, v94
	s_waitcnt vmcnt(4)
	ds_write_b32 v60, v95
	s_waitcnt vmcnt(3)
	ds_write_b32 v62, v96
	s_waitcnt vmcnt(2)
	ds_write_b32 v64, v97
	s_waitcnt vmcnt(1)
	ds_write_b32 v66, v98
	s_waitcnt vmcnt(0)
	ds_write_b32 v68, v99
	s_cbranch_scc1 .LBB0_18
; #define LAS __attribute__((address_space(3)))
; __device__ __forceinline__ unsigned pkbf(float lo, float hi) { return pg8::cvt_pk_bf16(lo, hi); }
;     ...
;     asm volatile("s_waitcnt lgkmcnt(0)" ::: "memory");
;     const int c = lane & 7;
; #pragma unroll
;     for (int j = 0; j < 4; ++j) { const int n = (lane >> 3) + 8 * j; const LAS float* s = scr + (8 * c) * 33 + n;
;         u32x4 o; o.x = pkbf(s[0 * 33] * sc, s[1 * 33] * sc); o.y = pkbf(s[2 * 33] * sc, s[3 * 33] * sc); o.z = pkbf(s[4 * 33] * sc, s[5 * 33] * sc); o.w = pkbf(s[6 * 33] * sc, s[7 * 33] * sc);
;         const int dn = ropeperm ? (n < 16 ? 2 * n : 2 * (n - 16) + 1) : n;
;         *(u32x4*)(WT + (size_t)(drow0 + dn) * ldk + kdst0 + k0 + 8 * c) = o; }
;     asm volatile("s_waitcnt lgkmcnt(0)" ::: "memory");
	s_waitcnt lgkmcnt(0)
	ds_read2_b32 v[32:33], v5 offset1:33
	s_waitcnt lgkmcnt(0)
	v_cvt_pk_bf16_f32 v32, v32, v33
	ds_read2_b32 v[34:35], v5 offset0:66 offset1:99
	s_mov_b32 s7, s1
	v_or_b32_e32 v6, s8, v3
	s_waitcnt lgkmcnt(0)
	v_cvt_pk_bf16_f32 v33, v34, v35
	ds_read2_b32 v[34:35], v5 offset0:132 offset1:165
	v_lshl_add_u64 v[42:43], s[6:7], 1, v[12:13]
	v_lshlrev_b32_e32 v6, 8, v6
	s_waitcnt lgkmcnt(0)
	v_cvt_pk_bf16_f32 v34, v34, v35
	ds_read2_b32 v[40:41], v5 offset0:198 offset1:231
	s_waitcnt lgkmcnt(0)
	v_cvt_pk_bf16_f32 v35, v40, v41
	v_lshl_add_u64 v[44:45], v[42:43], 0, v[6:7]
	ds_read2_b32 v[40:41], v5 offset0:8 offset1:41
	global_store_dwordx4 v[44:45], v[32:35], off
	v_or_b32_e32 v6, s8, v9
	v_lshlrev_b32_e32 v6, 8, v6
	s_waitcnt lgkmcnt(0)
	v_cvt_pk_bf16_f32 v32, v40, v41
	ds_read2_b32 v[34:35], v5 offset0:74 offset1:107
	s_waitcnt lgkmcnt(0)
	v_cvt_pk_bf16_f32 v33, v34, v35
	ds_read2_b32 v[34:35], v5 offset0:140 offset1:173
	s_waitcnt lgkmcnt(0)
	v_cvt_pk_bf16_f32 v34, v34, v35
	ds_read2_b32 v[40:41], v5 offset0:206 offset1:239
	s_waitcnt lgkmcnt(0)
	v_cvt_pk_bf16_f32 v35, v40, v41
	v_lshl_add_u64 v[44:45], v[42:43], 0, v[6:7]
	ds_read2_b32 v[40:41], v5 offset0:16 offset1:49
	global_store_dwordx4 v[44:45], v[32:35], off
	v_or_b32_e32 v6, s8, v11
	v_lshlrev_b32_e32 v6, 8, v6
	s_waitcnt lgkmcnt(0)
	v_cvt_pk_bf16_f32 v32, v40, v41
	ds_read2_b32 v[34:35], v5 offset0:82 offset1:115
	s_waitcnt lgkmcnt(0)
	v_cvt_pk_bf16_f32 v33, v34, v35
	ds_read2_b32 v[34:35], v5 offset0:148 offset1:181
	s_waitcnt lgkmcnt(0)
	v_cvt_pk_bf16_f32 v34, v34, v35
	ds_read2_b32 v[40:41], v5 offset0:214 offset1:247
	s_waitcnt lgkmcnt(0)
	v_cvt_pk_bf16_f32 v35, v40, v41
	v_lshl_add_u64 v[44:45], v[42:43], 0, v[6:7]
	ds_read2_b32 v[40:41], v5 offset0:24 offset1:57
	global_store_dwordx4 v[44:45], v[32:35], off
	v_or_b32_e32 v6, s8, v36
	v_lshlrev_b32_e32 v6, 8, v6
	s_waitcnt lgkmcnt(0)
	v_cvt_pk_bf16_f32 v32, v40, v41
	ds_read2_b32 v[34:35], v5 offset0:90 offset1:123
	s_waitcnt lgkmcnt(0)
	v_cvt_pk_bf16_f32 v33, v34, v35
	ds_read2_b32 v[34:35], v5 offset0:156 offset1:189
	s_waitcnt lgkmcnt(0)
	v_cvt_pk_bf16_f32 v34, v34, v35
	ds_read2_b32 v[40:41], v5 offset0:222 offset1:255
	s_waitcnt lgkmcnt(0)
	v_cvt_pk_bf16_f32 v35, v40, v41
	v_lshl_add_u64 v[40:41], v[42:43], 0, v[6:7]
	global_store_dwordx4 v[40:41], v[32:35], off
	s_waitcnt lgkmcnt(0)
	s_mov_b64 s[6:7], 0

; #pragma unroll 8
;     for (int i = 0; i < 32; ++i) { const int kk = 2 * i + (lane >> 5); scr[kk * 33 + (lane & 31)] = W[(size_t)(k0 + kk) * N + n0 + (lane & 31)]; }
.LBB0_22:
	s_lshl_b32 s14, s9, 1
	s_lshl_b32 s15, s10, 1
	v_or_b32_e32 v6, s15, v2
	s_add_i32 s16, s14, 4
	s_add_i32 s17, s15, 4
	v_mov_b32_e32 v41, v7
	v_or_b32_e32 v34, s14, v1
	s_add_i32 s20, s14, 8
	s_add_i32 s21, s15, 8
	s_add_i32 s24, s14, 12
	s_add_i32 s25, s15, 12
	s_add_i32 s26, s14, 16
	s_add_i32 s27, s15, 16
	s_add_i32 s28, s14, 20
	s_add_i32 s29, s15, 20
	s_add_i32 s30, s14, 24
	s_add_i32 s31, s15, 24
	s_add_i32 s68, s14, 28
	s_add_i32 s69, s15, 28
	v_lshlrev_b64 v[56:57], 11, v[6:7]
	v_mad_u64_u32 v[58:59], s[14:15], v6, s3, v[8:9]
	v_or_b32_e32 v40, s16, v1
	v_or_b32_e32 v6, s17, v2
	v_mov_b32_e32 v35, v7
	v_mov_b32_e32 v43, v7
	v_mov_b32_e32 v49, v7
	v_mov_b32_e32 v51, v7
	v_or_b32_e32 v42, s20, v1
	v_or_b32_e32 v48, s28, v1
	v_or_b32_e32 v50, s30, v1
	v_lshlrev_b64 v[60:61], 11, v[40:41]
	v_lshlrev_b64 v[62:63], 11, v[6:7]
	v_mad_u64_u32 v[64:65], s[14:15], v6, s3, v[8:9]
	v_or_b32_e32 v6, s21, v2
	v_mov_b32_e32 v45, v7
	v_mov_b32_e32 v47, v7
	v_mov_b32_e32 v53, v7
	v_lshlrev_b64 v[54:55], 11, v[34:35]
	v_or_b32_e32 v44, s24, v1
	v_or_b32_e32 v46, s26, v1
	v_or_b32_e32 v52, s68, v1
	v_lshl_add_u64 v[56:57], v[32:33], 0, v[56:57]
	v_lshlrev_b64 v[66:67], 11, v[42:43]
	v_lshlrev_b64 v[72:73], 11, v[48:49]
	v_lshlrev_b64 v[74:75], 11, v[50:51]
	v_lshl_add_u64 v[60:61], v[32:33], 0, v[60:61]
	v_lshlrev_b64 v[78:79], 11, v[6:7]
	v_mad_u64_u32 v[80:81], s[14:15], v6, s3, v[8:9]
	v_or_b32_e32 v6, s25, v2
	v_lshl_add_u64 v[54:55], v[32:33], 0, v[54:55]
	v_lshlrev_b64 v[68:69], 11, v[44:45]
	v_lshlrev_b64 v[70:71], 11, v[46:47]
	v_lshlrev_b64 v[76:77], 11, v[52:53]
	v_lshl_add_u64 v[62:63], v[32:33], 0, v[62:63]
	v_lshl_add_u64 v[66:67], v[32:33], 0, v[66:67]
	v_lshl_add_u64 v[72:73], v[32:33], 0, v[72:73]
	v_lshl_add_u64 v[74:75], v[32:33], 0, v[74:75]
	global_load_dword v39, v[56:57], off nt
	global_load_dword v59, v[54:55], off nt
	global_load_dword v65, v[62:63], off nt
	global_load_dword v81, v[60:61], off nt
	v_lshlrev_b64 v[56:57], 11, v[6:7]
	v_mad_u64_u32 v[60:61], s[14:15], v6, s3, v[8:9]
	v_or_b32_e32 v6, s27, v2
	v_lshl_add_u64 v[68:69], v[32:33], 0, v[68:69]
	v_lshl_add_u64 v[70:71], v[32:33], 0, v[70:71]
	v_lshl_add_u64 v[76:77], v[32:33], 0, v[76:77]
	v_lshl_add_u64 v[54:55], v[32:33], 0, v[78:79]
	global_load_dword v61, v[66:67], off nt
	global_load_dword v78, v[68:69], off nt
	global_load_dword v79, v[70:71], off nt
	s_nop 0
	global_load_dword v72, v[72:73], off nt
	s_nop 0
	global_load_dword v73, v[74:75], off nt
	s_nop 0
	global_load_dword v74, v[76:77], off nt
	v_lshl_add_u64 v[56:57], v[32:33], 0, v[56:57]
	v_lshlrev_b64 v[62:63], 11, v[6:7]
	v_mad_u64_u32 v[66:67], s[14:15], v6, s3, v[8:9]
	v_or_b32_e32 v6, s29, v2
	global_load_dword v67, v[54:55], off nt
	global_load_dword v75, v[56:57], off nt
	v_lshl_add_u64 v[54:55], v[32:33], 0, v[62:63]
	v_lshlrev_b64 v[56:57], 11, v[6:7]
	v_mad_u64_u32 v[62:63], s[14:15], v6, s3, v[8:9]
	v_or_b32_e32 v6, s31, v2
	v_mad_u64_u32 v[70:71], s[14:15], v6, s3, v[8:9]
	v_lshl_add_u64 v[56:57], v[32:33], 0, v[56:57]
	global_load_dword v63, v[54:55], off nt
	global_load_dword v71, v[56:57], off nt
	v_lshlrev_b64 v[68:69], 11, v[6:7]
	v_or_b32_e32 v6, s69, v2
	v_lshl_add_u64 v[54:55], v[32:33], 0, v[68:69]
	v_lshlrev_b64 v[56:57], 11, v[6:7]
	global_load_dword v68, v[54:55], off nt
	v_lshl_add_u64 v[54:55], v[32:33], 0, v[56:57]
	global_load_dword v56, v[54:55], off nt
	s_add_i32 s10, s10, 16
	s_add_i32 s9, s9, 16
	s_add_i32 s11, s11, -16
	s_cmp_lg_u32 s11, 0
	v_mad_u64_u32 v[34:35], s[14:15], v34, s3, v[8:9]
	v_mad_u64_u32 v[40:41], s[14:15], v40, s3, v[8:9]
	v_mad_u64_u32 v[42:43], s[14:15], v42, s3, v[8:9]
	v_mad_u64_u32 v[44:45], s[14:15], v44, s3, v[8:9]
	v_mad_u64_u32 v[46:47], s[14:15], v46, s3, v[8:9]
	v_mad_u64_u32 v[48:49], s[14:15], v48, s3, v[8:9]
	v_mad_u64_u32 v[50:51], s[14:15], v50, s3, v[8:9]
	v_mad_u64_u32 v[52:53], s[14:15], v52, s3, v[8:9]
	v_mad_u64_u32 v[54:55], s[14:15], v6, s3, v[8:9]
	s_waitcnt vmcnt(15)
	ds_write_b32 v58, v39
	s_waitcnt vmcnt(14)
	ds_write_b32 v34, v59
	s_waitcnt vmcnt(13)
	ds_write_b32 v64, v65
	s_waitcnt vmcnt(12)
	ds_write_b32 v40, v81
	s_waitcnt vmcnt(5)
	ds_write_b32 v80, v67
	ds_write_b32 v42, v61
	s_waitcnt vmcnt(4)
	ds_write_b32 v60, v75
	ds_write_b32 v44, v78
	s_waitcnt vmcnt(3)
	ds_write_b32 v66, v63
	ds_write_b32 v46, v79
	s_waitcnt vmcnt(2)
	ds_write_b32 v62, v71
	ds_write_b32 v48, v72
	s_waitcnt vmcnt(1)
	ds_write_b32 v70, v68
	ds_write_b32 v50, v73
	s_waitcnt vmcnt(0)
	ds_write_b32 v54, v56
	ds_write_b32 v52, v74
	s_cbranch_scc1 .LBB0_22
; #define LAS __attribute__((address_space(3)))
; __device__ __forceinline__ unsigned pkbf(float lo, float hi) { return pg8::cvt_pk_bf16(lo, hi); }
;     ...
;     asm volatile("s_waitcnt lgkmcnt(0)" ::: "memory");
;     const int c = lane & 7;
; #pragma unroll
;     for (int j = 0; j < 4; ++j) { const int n = (lane >> 3) + 8 * j; const LAS float* s = scr + (8 * c) * 33 + n;
;         u32x4 o; o.x = pkbf(s[0 * 33] * sc, s[1 * 33] * sc); o.y = pkbf(s[2 * 33] * sc, s[3 * 33] * sc); o.z = pkbf(s[4 * 33] * sc, s[5 * 33] * sc); o.w = pkbf(s[6 * 33] * sc, s[7 * 33] * sc);
;         const int dn = ropeperm ? (n < 16 ? 2 * n : 2 * (n - 16) + 1) : n;
;         *(u32x4*)(WT + (size_t)(drow0 + dn) * ldk + kdst0 + k0 + 8 * c) = o; }
;     asm volatile("s_waitcnt lgkmcnt(0)" ::: "memory");
; __device__ __forceinline__ void prologue(const P& p, LAS unsigned char* lds, int gw, int NGW, int wave, int lane, int gtid, int GT, int which) {
;     ...
;         bf16_t* WL = (bf16_t*)(ws + WS_WL);
;         if (r < 4 * I_L) { const int which = r / I_L, nb = r % I_L, d = which & 1; const bool isa = which >= 2;
;             transpose_item(p.in[isa ? 17 : 15] + (size_t)d * 64 * 512, 512, 0, nb * 32, WL + (isa ? 131072 : 0), 128, d * 64, d * 512 + nb * 32, false, scr, lane); continue; }
	s_and_b64 s[6:7], s[6:7], exec
	s_cselect_b32 s6, 0, 0x40000
	s_add_u32 s6, s33, s6
	s_addc_u32 s7, s35, 0
	s_lshl_b32 s9, s0, 9
	s_waitcnt lgkmcnt(0)
	s_lshl_b32 s0, s0, 7
	s_or_b32 s8, s9, s8
	ds_read2_b32 v[32:33], v5 offset1:33
	s_add_u32 s6, s6, s0
	s_waitcnt lgkmcnt(0)
	v_cvt_pk_bf16_f32 v32, v32, v33
	ds_read2_b32 v[34:35], v5 offset0:66 offset1:99
	v_lshlrev_b32_e32 v6, 1, v10
	v_or_b32_e32 v39, s8, v3
	s_addc_u32 s7, s7, 0
	s_waitcnt lgkmcnt(0)
	v_cvt_pk_bf16_f32 v33, v34, v35
	ds_read2_b32 v[34:35], v5 offset0:132 offset1:165
	v_lshl_add_u64 v[42:43], s[6:7], 0, v[6:7]
	v_lshlrev_b32_e32 v6, 8, v39
	s_waitcnt lgkmcnt(0)
	v_cvt_pk_bf16_f32 v34, v34, v35
	ds_read2_b32 v[40:41], v5 offset0:198 offset1:231
	s_waitcnt lgkmcnt(0)
	v_cvt_pk_bf16_f32 v35, v40, v41
	v_lshl_add_u64 v[44:45], v[42:43], 0, v[6:7]
	ds_read2_b32 v[40:41], v5 offset0:8 offset1:41
	global_store_dwordx4 v[44:45], v[32:35], off
	v_or_b32_e32 v6, s8, v9
	v_lshlrev_b32_e32 v6, 8, v6
	s_waitcnt lgkmcnt(0)
	v_cvt_pk_bf16_f32 v32, v40, v41
	ds_read2_b32 v[34:35], v5 offset0:74 offset1:107
	s_waitcnt lgkmcnt(0)
	v_cvt_pk_bf16_f32 v33, v34, v35
	ds_read2_b32 v[34:35], v5 offset0:140 offset1:173
	s_waitcnt lgkmcnt(0)
	v_cvt_pk_bf16_f32 v34, v34, v35
	ds_read2_b32 v[40:41], v5 offset0:206 offset1:239
	s_waitcnt lgkmcnt(0)
	v_cvt_pk_bf16_f32 v35, v40, v41
	v_lshl_add_u64 v[44:45], v[42:43], 0, v[6:7]
	ds_read2_b32 v[40:41], v5 offset0:16 offset1:49
	global_store_dwordx4 v[44:45], v[32:35], off
	v_or_b32_e32 v6, s8, v11
	v_lshlrev_b32_e32 v6, 8, v6
	s_waitcnt lgkmcnt(0)
	v_cvt_pk_bf16_f32 v32, v40, v41
	ds_read2_b32 v[34:35], v5 offset0:82 offset1:115
	s_waitcnt lgkmcnt(0)
	v_cvt_pk_bf16_f32 v33, v34, v35
	ds_read2_b32 v[34:35], v5 offset0:148 offset1:181
	s_waitcnt lgkmcnt(0)
	v_cvt_pk_bf16_f32 v34, v34, v35
	ds_read2_b32 v[40:41], v5 offset0:214 offset1:247
	s_waitcnt lgkmcnt(0)
	v_cvt_pk_bf16_f32 v35, v40, v41
	v_lshl_add_u64 v[44:45], v[42:43], 0, v[6:7]
	ds_read2_b32 v[40:41], v5 offset0:24 offset1:57
	global_store_dwordx4 v[44:45], v[32:35], off
	v_or_b32_e32 v6, s8, v36
	v_lshlrev_b32_e32 v6, 8, v6
	s_waitcnt lgkmcnt(0)
	v_cvt_pk_bf16_f32 v32, v40, v41
	ds_read2_b32 v[34:35], v5 offset0:90 offset1:123
	s_waitcnt lgkmcnt(0)
	v_cvt_pk_bf16_f32 v33, v34, v35
	ds_read2_b32 v[34:35], v5 offset0:156 offset1:189
	s_waitcnt lgkmcnt(0)
	v_cvt_pk_bf16_f32 v34, v34, v35
	ds_read2_b32 v[40:41], v5 offset0:222 offset1:255
	s_waitcnt lgkmcnt(0)
	v_cvt_pk_bf16_f32 v35, v40, v41
	v_lshl_add_u64 v[40:41], v[42:43], 0, v[6:7]
	global_store_dwordx4 v[40:41], v[32:35], off
	s_waitcnt lgkmcnt(0)

; #pragma unroll 8
;     for (int i = 0; i < 32; ++i) { const int kk = 2 * i + (lane >> 5); scr[kk * 33 + (lane & 31)] = W[(size_t)(k0 + kk) * N + n0 + (lane & 31)]; }
.LBB0_27:
	s_lshl_b32 s11, s7, 1
	s_lshl_b32 s14, s9, 1
	v_or_b32_e32 v6, s11, v1
	v_or_b32_e32 v39, s14, v2
	s_add_i32 s15, s11, 4
	s_add_i32 s16, s14, 4
	s_add_i32 s17, s11, 8
	s_add_i32 s20, s14, 8
	s_add_i32 s21, s11, 12
	s_add_i32 s24, s14, 12
	s_add_i32 s25, s11, 16
	s_add_i32 s26, s14, 16
	s_add_i32 s27, s11, 20
	s_add_i32 s28, s14, 20
	s_add_i32 s29, s11, 24
	s_add_i32 s30, s14, 24
	s_add_i32 s11, s11, 28
	s_add_i32 s14, s14, 28
	v_add_u32_e32 v40, s6, v39
	v_or_b32_e32 v70, s15, v1
	v_or_b32_e32 v71, s16, v2
	v_or_b32_e32 v72, s17, v1
	v_or_b32_e32 v73, s20, v2
	v_or_b32_e32 v74, s21, v1
	v_or_b32_e32 v75, s24, v2
	v_or_b32_e32 v76, s25, v1
	v_or_b32_e32 v77, s26, v2
	v_or_b32_e32 v78, s27, v1
	v_or_b32_e32 v79, s28, v2
	v_or_b32_e32 v80, s29, v1
	v_or_b32_e32 v81, s30, v2
	v_or_b32_e32 v82, s11, v1
	v_or_b32_e32 v83, s14, v2
	v_add_u32_e32 v34, s0, v6
	v_ashrrev_i32_e32 v41, 31, v40
	v_add_u32_e32 v42, s0, v70
	v_add_u32_e32 v44, s6, v71
	v_add_u32_e32 v46, s0, v72
	v_add_u32_e32 v48, s6, v73
	v_add_u32_e32 v50, s0, v74
	v_add_u32_e32 v52, s6, v75
	v_add_u32_e32 v54, s0, v76
	v_add_u32_e32 v56, s6, v77
	v_add_u32_e32 v58, s0, v78
	v_add_u32_e32 v60, s6, v79
	v_add_u32_e32 v62, s0, v80
	v_add_u32_e32 v64, s6, v81
	v_add_u32_e32 v66, s0, v82
	v_add_u32_e32 v68, s6, v83
	v_ashrrev_i32_e32 v35, 31, v34
	v_lshlrev_b64 v[40:41], 12, v[40:41]
	v_ashrrev_i32_e32 v45, 31, v44
	v_ashrrev_i32_e32 v43, 31, v42
	v_ashrrev_i32_e32 v49, 31, v48
	v_ashrrev_i32_e32 v47, 31, v46
	v_ashrrev_i32_e32 v53, 31, v52
	v_ashrrev_i32_e32 v51, 31, v50
	v_ashrrev_i32_e32 v57, 31, v56
	v_ashrrev_i32_e32 v55, 31, v54
	v_ashrrev_i32_e32 v61, 31, v60
	v_ashrrev_i32_e32 v59, 31, v58
	v_ashrrev_i32_e32 v65, 31, v64
	v_ashrrev_i32_e32 v63, 31, v62
	v_ashrrev_i32_e32 v69, 31, v68
	v_ashrrev_i32_e32 v67, 31, v66
	v_lshlrev_b64 v[34:35], 12, v[34:35]
	v_lshl_add_u64 v[40:41], v[32:33], 0, v[40:41]
	v_lshlrev_b64 v[42:43], 12, v[42:43]
	v_lshlrev_b64 v[44:45], 12, v[44:45]
	v_lshlrev_b64 v[46:47], 12, v[46:47]
	v_lshlrev_b64 v[48:49], 12, v[48:49]
	v_lshlrev_b64 v[50:51], 12, v[50:51]
	v_lshlrev_b64 v[52:53], 12, v[52:53]
	v_lshlrev_b64 v[54:55], 12, v[54:55]
	v_lshlrev_b64 v[56:57], 12, v[56:57]
	v_lshlrev_b64 v[58:59], 12, v[58:59]
	v_lshlrev_b64 v[60:61], 12, v[60:61]
	v_lshlrev_b64 v[62:63], 12, v[62:63]
	v_lshlrev_b64 v[64:65], 12, v[64:65]
	v_lshlrev_b64 v[66:67], 12, v[66:67]
	v_lshlrev_b64 v[68:69], 12, v[68:69]
	v_lshl_add_u64 v[34:35], v[32:33], 0, v[34:35]
	v_lshl_add_u64 v[44:45], v[32:33], 0, v[44:45]
	v_lshl_add_u64 v[42:43], v[32:33], 0, v[42:43]
	v_lshl_add_u64 v[48:49], v[32:33], 0, v[48:49]
	v_lshl_add_u64 v[46:47], v[32:33], 0, v[46:47]
	v_lshl_add_u64 v[52:53], v[32:33], 0, v[52:53]
	v_lshl_add_u64 v[50:51], v[32:33], 0, v[50:51]
	v_lshl_add_u64 v[56:57], v[32:33], 0, v[56:57]
	v_lshl_add_u64 v[54:55], v[32:33], 0, v[54:55]
	v_lshl_add_u64 v[60:61], v[32:33], 0, v[60:61]
	v_lshl_add_u64 v[58:59], v[32:33], 0, v[58:59]
	v_lshl_add_u64 v[64:65], v[32:33], 0, v[64:65]
	v_lshl_add_u64 v[62:63], v[32:33], 0, v[62:63]
	v_lshl_add_u64 v[68:69], v[32:33], 0, v[68:69]
	v_lshl_add_u64 v[66:67], v[32:33], 0, v[66:67]
	global_load_dword v84, v[40:41], off nt
	global_load_dword v85, v[34:35], off nt
	global_load_dword v86, v[44:45], off nt
	global_load_dword v87, v[42:43], off nt
	global_load_dword v88, v[48:49], off nt
	global_load_dword v89, v[46:47], off nt
	global_load_dword v90, v[52:53], off nt
	global_load_dword v91, v[50:51], off nt
	global_load_dword v92, v[56:57], off nt
	global_load_dword v93, v[54:55], off nt
	global_load_dword v94, v[60:61], off nt
	global_load_dword v95, v[58:59], off nt
	global_load_dword v96, v[64:65], off nt
	global_load_dword v97, v[62:63], off nt
	global_load_dword v98, v[68:69], off nt
	global_load_dword v99, v[66:67], off nt
	s_add_i32 s9, s9, 16
	s_add_i32 s7, s7, 16
	s_add_i32 s10, s10, -16
	v_mad_u64_u32 v[34:35], s[14:15], v39, s3, v[8:9]
	s_cmp_lg_u32 s10, 0
	v_mad_u64_u32 v[40:41], s[14:15], v6, s3, v[8:9]
	v_mad_u64_u32 v[42:43], s[14:15], v71, s3, v[8:9]
	v_mad_u64_u32 v[44:45], s[14:15], v70, s3, v[8:9]
	v_mad_u64_u32 v[46:47], s[14:15], v73, s3, v[8:9]
	v_mad_u64_u32 v[48:49], s[14:15], v72, s3, v[8:9]
	v_mad_u64_u32 v[50:51], s[14:15], v75, s3, v[8:9]
	v_mad_u64_u32 v[52:53], s[14:15], v74, s3, v[8:9]
	v_mad_u64_u32 v[54:55], s[14:15], v77, s3, v[8:9]
	v_mad_u64_u32 v[56:57], s[14:15], v76, s3, v[8:9]
	v_mad_u64_u32 v[58:59], s[14:15], v79, s3, v[8:9]
	v_mad_u64_u32 v[60:61], s[14:15], v78, s3, v[8:9]
	v_mad_u64_u32 v[62:63], s[14:15], v81, s3, v[8:9]
	v_mad_u64_u32 v[64:65], s[14:15], v80, s3, v[8:9]
	v_mad_u64_u32 v[66:67], s[14:15], v83, s3, v[8:9]
	v_mad_u64_u32 v[68:69], s[14:15], v82, s3, v[8:9]
	s_waitcnt vmcnt(15)
	ds_write_b32 v34, v84
	s_waitcnt vmcnt(14)
	ds_write_b32 v40, v85
	s_waitcnt vmcnt(13)
	ds_write_b32 v42, v86
	s_waitcnt vmcnt(12)
	ds_write_b32 v44, v87
	s_waitcnt vmcnt(11)
	ds_write_b32 v46, v88
	s_waitcnt vmcnt(10)
	ds_write_b32 v48, v89
	s_waitcnt vmcnt(9)
	ds_write_b32 v50, v90
	s_waitcnt vmcnt(8)
	ds_write_b32 v52, v91
	s_waitcnt vmcnt(7)
	ds_write_b32 v54, v92
	s_waitcnt vmcnt(6)
	ds_write_b32 v56, v93
	s_waitcnt vmcnt(5)
	ds_write_b32 v58, v94
	s_waitcnt vmcnt(4)
	ds_write_b32 v60, v95
	s_waitcnt vmcnt(3)
	ds_write_b32 v62, v96
	s_waitcnt vmcnt(2)
	ds_write_b32 v64, v97
	s_waitcnt vmcnt(1)
	ds_write_b32 v66, v98
	s_waitcnt vmcnt(0)
	ds_write_b32 v68, v99
	s_cbranch_scc1 .LBB0_27
; #define LAS __attribute__((address_space(3)))
; __device__ __forceinline__ unsigned pkbf(float lo, float hi) { return pg8::cvt_pk_bf16(lo, hi); }
;     ...
;     asm volatile("s_waitcnt lgkmcnt(0)" ::: "memory");
;     const int c = lane & 7;
; #pragma unroll
;     for (int j = 0; j < 4; ++j) { const int n = (lane >> 3) + 8 * j; const LAS float* s = scr + (8 * c) * 33 + n;
;         u32x4 o; o.x = pkbf(s[0 * 33] * sc, s[1 * 33] * sc); o.y = pkbf(s[2 * 33] * sc, s[3 * 33] * sc); o.z = pkbf(s[4 * 33] * sc, s[5 * 33] * sc); o.w = pkbf(s[6 * 33] * sc, s[7 * 33] * sc);
;         const int dn = ropeperm ? (n < 16 ? 2 * n : 2 * (n - 16) + 1) : n;
;         *(u32x4*)(WT + (size_t)(drow0 + dn) * ldk + kdst0 + k0 + 8 * c) = o; }
;     asm volatile("s_waitcnt lgkmcnt(0)" ::: "memory");
; __device__ __forceinline__ void prologue(const P& p, LAS unsigned char* lds, int gw, int NGW, int wave, int lane, int gtid, int GT, int which) {
;     ...
;         if (r < I_OUT) { const int kb = r / 32, nb = r % 32; transpose_item(p.in[24], DM, kb * 64, nb * 32, (bf16_t*)(ws + WS_WOUT), DM, 0, nb * 32, false, scr, lane); continue; }
	s_waitcnt lgkmcnt(0)
	ds_read2_b32 v[32:33], v5 offset1:33
	s_waitcnt lgkmcnt(0)
	v_cvt_pk_bf16_f32 v32, v32, v33
	ds_read2_b32 v[34:35], v5 offset0:66 offset1:99
	s_mov_b32 s7, s1
	v_or_b32_e32 v6, s8, v3
	s_waitcnt lgkmcnt(0)
	v_cvt_pk_bf16_f32 v33, v34, v35
	ds_read2_b32 v[34:35], v5 offset0:132 offset1:165
	v_lshl_add_u64 v[42:43], s[6:7], 1, v[14:15]
	v_lshlrev_b32_e32 v6, 11, v6
	s_waitcnt lgkmcnt(0)
	v_cvt_pk_bf16_f32 v34, v34, v35
	ds_read2_b32 v[40:41], v5 offset0:198 offset1:231
	s_waitcnt lgkmcnt(0)
	v_cvt_pk_bf16_f32 v35, v40, v41
	v_lshl_add_u64 v[44:45], v[42:43], 0, v[6:7]
	ds_read2_b32 v[40:41], v5 offset0:8 offset1:41
	global_store_dwordx4 v[44:45], v[32:35], off
	v_or_b32_e32 v6, s8, v9
	v_lshlrev_b32_e32 v6, 11, v6
	s_waitcnt lgkmcnt(0)
	v_cvt_pk_bf16_f32 v32, v40, v41
	ds_read2_b32 v[34:35], v5 offset0:74 offset1:107
	s_waitcnt lgkmcnt(0)
	v_cvt_pk_bf16_f32 v33, v34, v35
	ds_read2_b32 v[34:35], v5 offset0:140 offset1:173
	s_waitcnt lgkmcnt(0)
	v_cvt_pk_bf16_f32 v34, v34, v35
	ds_read2_b32 v[40:41], v5 offset0:206 offset1:239
	s_waitcnt lgkmcnt(0)
	v_cvt_pk_bf16_f32 v35, v40, v41
	v_lshl_add_u64 v[44:45], v[42:43], 0, v[6:7]
	ds_read2_b32 v[40:41], v5 offset0:16 offset1:49
	global_store_dwordx4 v[44:45], v[32:35], off
	v_or_b32_e32 v6, s8, v11
	v_lshlrev_b32_e32 v6, 11, v6
	s_waitcnt lgkmcnt(0)
	v_cvt_pk_bf16_f32 v32, v40, v41
	ds_read2_b32 v[34:35], v5 offset0:82 offset1:115
	s_waitcnt lgkmcnt(0)
	v_cvt_pk_bf16_f32 v33, v34, v35
	ds_read2_b32 v[34:35], v5 offset0:148 offset1:181
	s_waitcnt lgkmcnt(0)
	v_cvt_pk_bf16_f32 v34, v34, v35
	ds_read2_b32 v[40:41], v5 offset0:214 offset1:247
	s_waitcnt lgkmcnt(0)
	v_cvt_pk_bf16_f32 v35, v40, v41
	v_lshl_add_u64 v[44:45], v[42:43], 0, v[6:7]
	ds_read2_b32 v[40:41], v5 offset0:24 offset1:57
	global_store_dwordx4 v[44:45], v[32:35], off
	v_or_b32_e32 v6, s8, v36
	v_lshlrev_b32_e32 v6, 11, v6
	s_waitcnt lgkmcnt(0)
	v_cvt_pk_bf16_f32 v32, v40, v41
	ds_read2_b32 v[34:35], v5 offset0:90 offset1:123
	s_waitcnt lgkmcnt(0)
	v_cvt_pk_bf16_f32 v33, v34, v35
	ds_read2_b32 v[34:35], v5 offset0:156 offset1:189
	s_waitcnt lgkmcnt(0)
	v_cvt_pk_bf16_f32 v34, v34, v35
	ds_read2_b32 v[40:41], v5 offset0:222 offset1:255
	s_waitcnt lgkmcnt(0)
	v_cvt_pk_bf16_f32 v35, v40, v41
	v_lshl_add_u64 v[40:41], v[42:43], 0, v[6:7]
	global_store_dwordx4 v[40:41], v[32:35], off
	s_waitcnt lgkmcnt(0)

; #pragma unroll 8
;     for (int i = 0; i < 32; ++i) { const int kk = 2 * i + (lane >> 5); scr[kk * 33 + (lane & 31)] = W[(size_t)(k0 + kk) * N + n0 + (lane & 31)]; }
.LBB0_32:
	s_lshl_b32 s10, s7, 1
	s_lshl_b32 s11, s8, 1
	v_or_b32_e32 v6, s10, v1
	v_or_b32_e32 v39, s11, v2
	s_add_i32 s14, s10, 4
	s_add_i32 s15, s11, 4
	s_add_i32 s16, s10, 8
	s_add_i32 s17, s11, 8
	s_add_i32 s20, s10, 12
	s_add_i32 s21, s11, 12
	s_add_i32 s24, s10, 16
	s_add_i32 s25, s11, 16
	s_add_i32 s26, s10, 20
	s_add_i32 s27, s11, 20
	s_add_i32 s28, s10, 24
	s_add_i32 s29, s11, 24
	s_add_i32 s10, s10, 28
	s_add_i32 s11, s11, 28
	v_add_u32_e32 v40, s6, v39
	v_or_b32_e32 v70, s14, v1
	v_or_b32_e32 v71, s15, v2
	v_or_b32_e32 v72, s16, v1
	v_or_b32_e32 v73, s17, v2
	v_or_b32_e32 v74, s20, v1
	v_or_b32_e32 v75, s21, v2
	v_or_b32_e32 v76, s24, v1
	v_or_b32_e32 v77, s25, v2
	v_or_b32_e32 v78, s26, v1
	v_or_b32_e32 v79, s27, v2
	v_or_b32_e32 v80, s28, v1
	v_or_b32_e32 v81, s29, v2
	v_or_b32_e32 v82, s10, v1
	v_or_b32_e32 v83, s11, v2
	v_add_u32_e32 v34, s0, v6
	v_ashrrev_i32_e32 v41, 31, v40
	v_add_u32_e32 v42, s0, v70
	v_add_u32_e32 v44, s6, v71
	v_add_u32_e32 v46, s0, v72
	v_add_u32_e32 v48, s6, v73
	v_add_u32_e32 v50, s0, v74
	v_add_u32_e32 v52, s6, v75
	v_add_u32_e32 v54, s0, v76
	v_add_u32_e32 v56, s6, v77
	v_add_u32_e32 v58, s0, v78
	v_add_u32_e32 v60, s6, v79
	v_add_u32_e32 v62, s0, v80
	v_add_u32_e32 v64, s6, v81
	v_add_u32_e32 v66, s0, v82
	v_add_u32_e32 v68, s6, v83
	v_ashrrev_i32_e32 v35, 31, v34
	v_lshlrev_b64 v[40:41], 12, v[40:41]
	v_ashrrev_i32_e32 v45, 31, v44
	v_ashrrev_i32_e32 v43, 31, v42
	v_ashrrev_i32_e32 v49, 31, v48
	v_ashrrev_i32_e32 v47, 31, v46
	v_ashrrev_i32_e32 v53, 31, v52
	v_ashrrev_i32_e32 v51, 31, v50
	v_ashrrev_i32_e32 v57, 31, v56
	v_ashrrev_i32_e32 v55, 31, v54
	v_ashrrev_i32_e32 v61, 31, v60
	v_ashrrev_i32_e32 v59, 31, v58
	v_ashrrev_i32_e32 v65, 31, v64
	v_ashrrev_i32_e32 v63, 31, v62
	v_ashrrev_i32_e32 v69, 31, v68
	v_ashrrev_i32_e32 v67, 31, v66
	v_lshlrev_b64 v[34:35], 12, v[34:35]
	v_lshl_add_u64 v[40:41], v[32:33], 0, v[40:41]
	v_lshlrev_b64 v[42:43], 12, v[42:43]
	v_lshlrev_b64 v[44:45], 12, v[44:45]
	v_lshlrev_b64 v[46:47], 12, v[46:47]
	v_lshlrev_b64 v[48:49], 12, v[48:49]
	v_lshlrev_b64 v[50:51], 12, v[50:51]
	v_lshlrev_b64 v[52:53], 12, v[52:53]
	v_lshlrev_b64 v[54:55], 12, v[54:55]
	v_lshlrev_b64 v[56:57], 12, v[56:57]
	v_lshlrev_b64 v[58:59], 12, v[58:59]
	v_lshlrev_b64 v[60:61], 12, v[60:61]
	v_lshlrev_b64 v[62:63], 12, v[62:63]
	v_lshlrev_b64 v[64:65], 12, v[64:65]
	v_lshlrev_b64 v[66:67], 12, v[66:67]
	v_lshlrev_b64 v[68:69], 12, v[68:69]
	v_lshl_add_u64 v[34:35], v[32:33], 0, v[34:35]
	v_lshl_add_u64 v[44:45], v[32:33], 0, v[44:45]
	v_lshl_add_u64 v[42:43], v[32:33], 0, v[42:43]
	v_lshl_add_u64 v[48:49], v[32:33], 0, v[48:49]
	v_lshl_add_u64 v[46:47], v[32:33], 0, v[46:47]
	v_lshl_add_u64 v[52:53], v[32:33], 0, v[52:53]
	v_lshl_add_u64 v[50:51], v[32:33], 0, v[50:51]
	v_lshl_add_u64 v[56:57], v[32:33], 0, v[56:57]
	v_lshl_add_u64 v[54:55], v[32:33], 0, v[54:55]
	v_lshl_add_u64 v[60:61], v[32:33], 0, v[60:61]
	v_lshl_add_u64 v[58:59], v[32:33], 0, v[58:59]
	v_lshl_add_u64 v[64:65], v[32:33], 0, v[64:65]
	v_lshl_add_u64 v[62:63], v[32:33], 0, v[62:63]
	v_lshl_add_u64 v[68:69], v[32:33], 0, v[68:69]
	v_lshl_add_u64 v[66:67], v[32:33], 0, v[66:67]
	global_load_dword v84, v[40:41], off nt
	global_load_dword v85, v[34:35], off nt
	global_load_dword v86, v[44:45], off nt
	global_load_dword v87, v[42:43], off nt
	global_load_dword v88, v[48:49], off nt
	global_load_dword v89, v[46:47], off nt
	global_load_dword v90, v[52:53], off nt
	global_load_dword v91, v[50:51], off nt
	global_load_dword v92, v[56:57], off nt
	global_load_dword v93, v[54:55], off nt
	global_load_dword v94, v[60:61], off nt
	global_load_dword v95, v[58:59], off nt
	global_load_dword v96, v[64:65], off nt
	global_load_dword v97, v[62:63], off nt
	global_load_dword v98, v[68:69], off nt
	global_load_dword v99, v[66:67], off nt
	s_add_i32 s8, s8, 16
	s_add_i32 s7, s7, 16
	s_add_i32 s9, s9, -16
	v_mad_u64_u32 v[34:35], s[10:11], v39, s3, v[8:9]
	s_cmp_lg_u32 s9, 0
	v_mad_u64_u32 v[40:41], s[10:11], v6, s3, v[8:9]
	v_mad_u64_u32 v[42:43], s[10:11], v71, s3, v[8:9]
	v_mad_u64_u32 v[44:45], s[10:11], v70, s3, v[8:9]
	v_mad_u64_u32 v[46:47], s[10:11], v73, s3, v[8:9]
	v_mad_u64_u32 v[48:49], s[10:11], v72, s3, v[8:9]
	v_mad_u64_u32 v[50:51], s[10:11], v75, s3, v[8:9]
	v_mad_u64_u32 v[52:53], s[10:11], v74, s3, v[8:9]
	v_mad_u64_u32 v[54:55], s[10:11], v77, s3, v[8:9]
	v_mad_u64_u32 v[56:57], s[10:11], v76, s3, v[8:9]
	v_mad_u64_u32 v[58:59], s[10:11], v79, s3, v[8:9]
	v_mad_u64_u32 v[60:61], s[10:11], v78, s3, v[8:9]
	v_mad_u64_u32 v[62:63], s[10:11], v81, s3, v[8:9]
	v_mad_u64_u32 v[64:65], s[10:11], v80, s3, v[8:9]
	v_mad_u64_u32 v[66:67], s[10:11], v83, s3, v[8:9]
	v_mad_u64_u32 v[68:69], s[10:11], v82, s3, v[8:9]
	s_waitcnt vmcnt(15)
	ds_write_b32 v34, v84
	s_waitcnt vmcnt(14)
	ds_write_b32 v40, v85
	s_waitcnt vmcnt(13)
	ds_write_b32 v42, v86
	s_waitcnt vmcnt(12)
	ds_write_b32 v44, v87
	s_waitcnt vmcnt(11)
	ds_write_b32 v46, v88
	s_waitcnt vmcnt(10)
	ds_write_b32 v48, v89
	s_waitcnt vmcnt(9)
	ds_write_b32 v50, v90
	s_waitcnt vmcnt(8)
	ds_write_b32 v52, v91
	s_waitcnt vmcnt(7)
	ds_write_b32 v54, v92
	s_waitcnt vmcnt(6)
	ds_write_b32 v56, v93
	s_waitcnt vmcnt(5)
	ds_write_b32 v58, v94
	s_waitcnt vmcnt(4)
	ds_write_b32 v60, v95
	s_waitcnt vmcnt(3)
	ds_write_b32 v62, v96
	s_waitcnt vmcnt(2)
	ds_write_b32 v64, v97
	s_waitcnt vmcnt(1)
	ds_write_b32 v66, v98
	s_waitcnt vmcnt(0)
	ds_write_b32 v68, v99
	s_cbranch_scc1 .LBB0_32
; #define LAS __attribute__((address_space(3)))
; __device__ __forceinline__ unsigned pkbf(float lo, float hi) { return pg8::cvt_pk_bf16(lo, hi); }
;     ...
;     asm volatile("s_waitcnt lgkmcnt(0)" ::: "memory");
;     const int c = lane & 7;
; #pragma unroll
;     for (int j = 0; j < 4; ++j) { const int n = (lane >> 3) + 8 * j; const LAS float* s = scr + (8 * c) * 33 + n;
;         u32x4 o; o.x = pkbf(s[0 * 33] * sc, s[1 * 33] * sc); o.y = pkbf(s[2 * 33] * sc, s[3 * 33] * sc); o.z = pkbf(s[4 * 33] * sc, s[5 * 33] * sc); o.w = pkbf(s[6 * 33] * sc, s[7 * 33] * sc);
;         const int dn = ropeperm ? (n < 16 ? 2 * n : 2 * (n - 16) + 1) : n;
;         *(u32x4*)(WT + (size_t)(drow0 + dn) * ldk + kdst0 + k0 + 8 * c) = o; }
;     asm volatile("s_waitcnt lgkmcnt(0)" ::: "memory");
; __device__ __forceinline__ void prologue(const P& p, LAS unsigned char* lds, int gw, int NGW, int wave, int lane, int gtid, int GT, int which) {
;     ...
;         if (r < I_UKV) { const int kb = r / 32, nb = r % 32, h = nb >> 2, part = nb & 3; const int dr = part < 2 ? h * 64 + part * 32 : 512 + h * 64 + (part - 2) * 32;
;             transpose_item(p.in[11], 1024, kb * 64, nb * 32, (bf16_t*)(ws + WS_WUKV), 256, 0, dr, false, scr, lane); continue; }
	s_lshl_b32 s0, s67, 4
	s_and_b32 s0, s0, 0x1c0
	s_mov_b32 s7, s1
	s_add_i32 s8, s84, s0
	s_or_b32 s0, s0, s85
	s_waitcnt lgkmcnt(0)
	v_lshl_add_u64 v[40:41], s[6:7], 1, v[16:17]
	s_and_b64 s[6:7], s[4:5], exec
	ds_read2_b32 v[32:33], v5 offset1:33
	s_cselect_b32 s0, s0, s8
	s_waitcnt lgkmcnt(0)
	v_cvt_pk_bf16_f32 v32, v32, v33
	ds_read2_b32 v[34:35], v5 offset0:66 offset1:99
	v_or_b32_e32 v6, s0, v3
	s_waitcnt lgkmcnt(0)
	v_cvt_pk_bf16_f32 v33, v34, v35
	ds_read2_b32 v[34:35], v5 offset0:132 offset1:165
	v_lshlrev_b32_e32 v6, 9, v6
	s_waitcnt lgkmcnt(0)
	v_cvt_pk_bf16_f32 v34, v34, v35
	ds_read2_b32 v[42:43], v5 offset0:198 offset1:231
	s_waitcnt lgkmcnt(0)
	v_cvt_pk_bf16_f32 v35, v42, v43
	v_lshl_add_u64 v[44:45], v[40:41], 0, v[6:7]
	ds_read2_b32 v[42:43], v5 offset0:8 offset1:41
	global_store_dwordx4 v[44:45], v[32:35], off
	v_or_b32_e32 v6, s0, v9
	v_lshlrev_b32_e32 v6, 9, v6
	s_waitcnt lgkmcnt(0)
	v_cvt_pk_bf16_f32 v32, v42, v43
	ds_read2_b32 v[34:35], v5 offset0:74 offset1:107
	s_waitcnt lgkmcnt(0)
	v_cvt_pk_bf16_f32 v33, v34, v35
	ds_read2_b32 v[34:35], v5 offset0:140 offset1:173
	s_waitcnt lgkmcnt(0)
	v_cvt_pk_bf16_f32 v34, v34, v35
	ds_read2_b32 v[42:43], v5 offset0:206 offset1:239
	s_waitcnt lgkmcnt(0)
	v_cvt_pk_bf16_f32 v35, v42, v43
	v_lshl_add_u64 v[44:45], v[40:41], 0, v[6:7]
	ds_read2_b32 v[42:43], v5 offset0:16 offset1:49
	global_store_dwordx4 v[44:45], v[32:35], off
	v_or_b32_e32 v6, s0, v11
	v_lshlrev_b32_e32 v6, 9, v6
	s_waitcnt lgkmcnt(0)
	v_cvt_pk_bf16_f32 v32, v42, v43
	ds_read2_b32 v[34:35], v5 offset0:82 offset1:115
	s_waitcnt lgkmcnt(0)
	v_cvt_pk_bf16_f32 v33, v34, v35
	ds_read2_b32 v[34:35], v5 offset0:148 offset1:181
	s_waitcnt lgkmcnt(0)
	v_cvt_pk_bf16_f32 v34, v34, v35
	ds_read2_b32 v[42:43], v5 offset0:214 offset1:247
	s_waitcnt lgkmcnt(0)
	v_cvt_pk_bf16_f32 v35, v42, v43
	v_lshl_add_u64 v[44:45], v[40:41], 0, v[6:7]
	v_or_b32_e32 v6, s0, v36
	ds_read2_b32 v[42:43], v5 offset0:24 offset1:57
	global_store_dwordx4 v[44:45], v[32:35], off
	v_lshlrev_b32_e32 v6, 9, v6
	v_lshl_add_u64 v[40:41], v[40:41], 0, v[6:7]
	s_waitcnt lgkmcnt(0)
	v_cvt_pk_bf16_f32 v32, v42, v43
	ds_read2_b32 v[34:35], v5 offset0:90 offset1:123
	s_waitcnt lgkmcnt(0)
	v_cvt_pk_bf16_f32 v33, v34, v35
	ds_read2_b32 v[34:35], v5 offset0:156 offset1:189
	s_waitcnt lgkmcnt(0)
	v_cvt_pk_bf16_f32 v34, v34, v35
	ds_read2_b32 v[42:43], v5 offset0:222 offset1:255
	s_waitcnt lgkmcnt(0)
	v_cvt_pk_bf16_f32 v35, v42, v43
	global_store_dwordx4 v[40:41], v[32:35], off
	s_waitcnt lgkmcnt(0)

; #pragma unroll 8
;     for (int i = 0; i < 32; ++i) { const int kk = 2 * i + (lane >> 5); scr[kk * 33 + (lane & 31)] = W[(size_t)(k0 + kk) * N + n0 + (lane & 31)]; }
; __device__ __forceinline__ void prologue(const P& p, LAS unsigned char* lds, int gw, int NGW, int wave, int lane, int gtid, int GT, int which) {
;     ...
;         if (r < I_UQ) { const int kb = r / 24, nb = r % 24; transpose_item(p.in[9], 768, kb * 64, nb * 32, (bf16_t*)(ws + WS_WUQ), 384, 0, nb * 32, (nb % 3) == 2, scr, lane, 0.10206207261596575f * 1.4426950408889634f); continue; }
.LBB0_37:
	s_lshl_b32 s14, s9, 1
	s_lshl_b32 s15, s10, 1
	v_or_b32_e32 v6, s14, v1
	v_or_b32_e32 v39, s15, v2
	s_add_i32 s16, s14, 4
	s_add_i32 s17, s15, 4
	s_add_i32 s20, s14, 8
	s_add_i32 s21, s15, 8
	s_add_i32 s24, s14, 12
	s_add_i32 s25, s15, 12
	s_add_i32 s26, s14, 16
	s_add_i32 s27, s15, 16
	s_add_i32 s28, s14, 20
	s_add_i32 s29, s15, 20
	s_add_i32 s30, s14, 24
	s_add_i32 s31, s15, 24
	s_add_i32 s14, s14, 28
	s_add_i32 s15, s15, 28
	v_add_u32_e32 v34, s7, v39
	v_or_b32_e32 v70, s16, v1
	v_or_b32_e32 v71, s17, v2
	v_or_b32_e32 v72, s20, v1
	v_or_b32_e32 v73, s21, v2
	v_or_b32_e32 v74, s24, v1
	v_or_b32_e32 v75, s25, v2
	v_or_b32_e32 v76, s26, v1
	v_or_b32_e32 v77, s27, v2
	v_or_b32_e32 v78, s28, v1
	v_or_b32_e32 v79, s29, v2
	v_or_b32_e32 v80, s30, v1
	v_or_b32_e32 v81, s31, v2
	v_or_b32_e32 v82, s14, v1
	v_or_b32_e32 v83, s15, v2
	v_add_u32_e32 v40, s0, v6
	v_mad_u64_u32 v[34:35], s[14:15], v34, s87, v[32:33]
	v_add_u32_e32 v44, s0, v70
	v_add_u32_e32 v42, s7, v71
	v_add_u32_e32 v48, s0, v72
	v_add_u32_e32 v46, s7, v73
	v_add_u32_e32 v52, s0, v74
	v_add_u32_e32 v50, s7, v75
	v_add_u32_e32 v56, s0, v76
	v_add_u32_e32 v54, s7, v77
	v_add_u32_e32 v60, s0, v78
	v_add_u32_e32 v58, s7, v79
	v_add_u32_e32 v64, s0, v80
	v_add_u32_e32 v62, s7, v81
	v_add_u32_e32 v68, s0, v82
	v_add_u32_e32 v66, s7, v83
	v_mad_u64_u32 v[40:41], s[14:15], v40, s87, v[32:33]
	v_mad_u64_u32 v[42:43], s[14:15], v42, s87, v[32:33]
	v_mad_u64_u32 v[44:45], s[14:15], v44, s87, v[32:33]
	v_mad_u64_u32 v[46:47], s[14:15], v46, s87, v[32:33]
	v_mad_u64_u32 v[48:49], s[14:15], v48, s87, v[32:33]
	v_mad_u64_u32 v[50:51], s[14:15], v50, s87, v[32:33]
	v_mad_u64_u32 v[52:53], s[14:15], v52, s87, v[32:33]
	v_mad_u64_u32 v[54:55], s[14:15], v54, s87, v[32:33]
	v_mad_u64_u32 v[56:57], s[14:15], v56, s87, v[32:33]
	v_mad_u64_u32 v[58:59], s[14:15], v58, s87, v[32:33]
	v_mad_u64_u32 v[60:61], s[14:15], v60, s87, v[32:33]
	v_mad_u64_u32 v[62:63], s[14:15], v62, s87, v[32:33]
	v_mad_u64_u32 v[64:65], s[14:15], v64, s87, v[32:33]
	v_mad_u64_u32 v[66:67], s[14:15], v66, s87, v[32:33]
	v_mad_u64_u32 v[68:69], s[14:15], v68, s87, v[32:33]
	global_load_dword v84, v[34:35], off nt
	global_load_dword v85, v[40:41], off nt
	global_load_dword v86, v[42:43], off nt
	global_load_dword v87, v[44:45], off nt
	global_load_dword v88, v[46:47], off nt
	global_load_dword v89, v[48:49], off nt
	global_load_dword v90, v[50:51], off nt
	global_load_dword v91, v[52:53], off nt
	global_load_dword v92, v[54:55], off nt
	global_load_dword v93, v[56:57], off nt
	global_load_dword v94, v[58:59], off nt
	global_load_dword v95, v[60:61], off nt
	global_load_dword v96, v[62:63], off nt
	global_load_dword v97, v[64:65], off nt
	global_load_dword v98, v[66:67], off nt
	global_load_dword v99, v[68:69], off nt
	s_add_i32 s10, s10, 16
	s_add_i32 s9, s9, 16
	s_add_i32 s11, s11, -16
	v_mad_u64_u32 v[34:35], s[14:15], v39, s3, v[8:9]
	s_cmp_lg_u32 s11, 0
	v_mad_u64_u32 v[40:41], s[14:15], v6, s3, v[8:9]
	v_mad_u64_u32 v[42:43], s[14:15], v71, s3, v[8:9]
	v_mad_u64_u32 v[44:45], s[14:15], v70, s3, v[8:9]
	v_mad_u64_u32 v[46:47], s[14:15], v73, s3, v[8:9]
	v_mad_u64_u32 v[48:49], s[14:15], v72, s3, v[8:9]
	v_mad_u64_u32 v[50:51], s[14:15], v75, s3, v[8:9]
	v_mad_u64_u32 v[52:53], s[14:15], v74, s3, v[8:9]
	v_mad_u64_u32 v[54:55], s[14:15], v77, s3, v[8:9]
	v_mad_u64_u32 v[56:57], s[14:15], v76, s3, v[8:9]
	v_mad_u64_u32 v[58:59], s[14:15], v79, s3, v[8:9]
	v_mad_u64_u32 v[60:61], s[14:15], v78, s3, v[8:9]
	v_mad_u64_u32 v[62:63], s[14:15], v81, s3, v[8:9]
	v_mad_u64_u32 v[64:65], s[14:15], v80, s3, v[8:9]
	v_mad_u64_u32 v[66:67], s[14:15], v83, s3, v[8:9]
	v_mad_u64_u32 v[68:69], s[14:15], v82, s3, v[8:9]
	s_waitcnt vmcnt(15)
	ds_write_b32 v34, v84
	s_waitcnt vmcnt(14)
	ds_write_b32 v40, v85
	s_waitcnt vmcnt(13)
	ds_write_b32 v42, v86
	s_waitcnt vmcnt(12)
	ds_write_b32 v44, v87
	s_waitcnt vmcnt(11)
	ds_write_b32 v46, v88
	s_waitcnt vmcnt(10)
	ds_write_b32 v48, v89
	s_waitcnt vmcnt(9)
	ds_write_b32 v50, v90
	s_waitcnt vmcnt(8)
	ds_write_b32 v52, v91
	s_waitcnt vmcnt(7)
	ds_write_b32 v54, v92
	s_waitcnt vmcnt(6)
	ds_write_b32 v56, v93
	s_waitcnt vmcnt(5)
	ds_write_b32 v58, v94
	s_waitcnt vmcnt(4)
	ds_write_b32 v60, v95
	s_waitcnt vmcnt(3)
	ds_write_b32 v62, v96
	s_waitcnt vmcnt(2)
	ds_write_b32 v64, v97
	s_waitcnt vmcnt(1)
	ds_write_b32 v66, v98
	s_waitcnt vmcnt(0)
	ds_write_b32 v68, v99
	s_cbranch_scc1 .LBB0_37
; #define LAS __attribute__((address_space(3)))
; __device__ __forceinline__ unsigned pkbf(float lo, float hi) { return pg8::cvt_pk_bf16(lo, hi); }
;     ...
;     asm volatile("s_waitcnt lgkmcnt(0)" ::: "memory");
;     const int c = lane & 7;
; #pragma unroll
;     for (int j = 0; j < 4; ++j) { const int n = (lane >> 3) + 8 * j; const LAS float* s = scr + (8 * c) * 33 + n;
;         u32x4 o; o.x = pkbf(s[0 * 33] * sc, s[1 * 33] * sc); o.y = pkbf(s[2 * 33] * sc, s[3 * 33] * sc); o.z = pkbf(s[4 * 33] * sc, s[5 * 33] * sc); o.w = pkbf(s[6 * 33] * sc, s[7 * 33] * sc);
;         const int dn = ropeperm ? (n < 16 ? 2 * n : 2 * (n - 16) + 1) : n;
;         *(u32x4*)(WT + (size_t)(drow0 + dn) * ldk + kdst0 + k0 + 8 * c) = o; }
;     asm volatile("s_waitcnt lgkmcnt(0)" ::: "memory");
; __device__ __forceinline__ void prologue(const P& p, LAS unsigned char* lds, int gw, int NGW, int wave, int lane, int gtid, int GT, int which) {
;     ...
;         if (r < I_UQ) { const int kb = r / 24, nb = r % 24; transpose_item(p.in[9], 768, kb * 64, nb * 32, (bf16_t*)(ws + WS_WUQ), 384, 0, nb * 32, (nb % 3) == 2, scr, lane, 0.10206207261596575f * 1.4426950408889634f); continue; }
	s_waitcnt lgkmcnt(0)
	ds_read2_b32 v[32:33], v5 offset1:33
	s_mul_i32 s0, s8, 0xffab
	s_add_i32 s0, s0, 0xffaa
	s_and_b32 s0, s0, 0xff
	s_cmpk_lt_u32 s0, 0x55
	s_waitcnt lgkmcnt(0)
	v_mul_f32_e32 v6, 0x3e16c740, v32
	v_mul_f32_e32 v32, 0x3e16c740, v33
	v_cvt_pk_bf16_f32 v32, v6, v32
	ds_read2_b32 v[34:35], v5 offset0:66 offset1:99
	s_cselect_b64 vcc, -1, 0
	v_cndmask_b32_e64 v39, 0, 1, vcc
	s_lshl_b32 s0, s7, 1
	v_lshl_add_u64 v[42:43], v[18:19], 0, s[0:1]
	s_waitcnt lgkmcnt(0)
	v_mul_f32_e32 v33, 0x3e16c740, v35
	v_mul_f32_e32 v6, 0x3e16c740, v34
	v_cvt_pk_bf16_f32 v33, v6, v33
	ds_read2_b32 v[34:35], v5 offset0:132 offset1:165
	s_waitcnt lgkmcnt(0)
	v_mul_f32_e32 v6, 0x3e16c740, v34
	v_mul_f32_e32 v34, 0x3e16c740, v35
	v_cvt_pk_bf16_f32 v34, v6, v34
	ds_read2_b32 v[40:41], v5 offset0:198 offset1:231
	v_lshlrev_b32_e32 v6, v39, v3
	v_or_b32_e32 v6, s6, v6
	v_mul_u32_u24_e32 v6, 0x180, v6
	v_lshlrev_b32_e32 v6, 1, v6
	s_waitcnt lgkmcnt(0)
	v_mul_f32_e32 v35, 0x3e16c740, v40
	v_mul_f32_e32 v40, 0x3e16c740, v41
	v_cvt_pk_bf16_f32 v35, v35, v40
	ds_read2_b32 v[40:41], v5 offset0:8 offset1:41
	v_lshl_add_u64 v[44:45], v[42:43], 0, v[6:7]
	global_store_dwordx4 v[44:45], v[32:35], off
	s_waitcnt lgkmcnt(0)
	v_mul_f32_e32 v6, 0x3e16c740, v40
	v_mul_f32_e32 v32, 0x3e16c740, v41
	v_cvt_pk_bf16_f32 v32, v6, v32
	ds_read2_b32 v[34:35], v5 offset0:74 offset1:107
	s_waitcnt lgkmcnt(0)
	v_mul_f32_e32 v33, 0x3e16c740, v35
	v_mul_f32_e32 v6, 0x3e16c740, v34
	v_cvt_pk_bf16_f32 v33, v6, v33
	ds_read2_b32 v[34:35], v5 offset0:140 offset1:173
	s_waitcnt lgkmcnt(0)
	v_mul_f32_e32 v6, 0x3e16c740, v34
	v_mul_f32_e32 v34, 0x3e16c740, v35
	v_cvt_pk_bf16_f32 v34, v6, v34
	ds_read2_b32 v[40:41], v5 offset0:206 offset1:239
	v_lshlrev_b32_e32 v6, v39, v9
	v_or_b32_e32 v6, s6, v6
	v_mul_u32_u24_e32 v6, 0x180, v6
	v_lshlrev_b32_e32 v6, 1, v6
	s_waitcnt lgkmcnt(0)
	v_mul_f32_e32 v35, 0x3e16c740, v40
	v_mul_f32_e32 v39, 0x3e16c740, v41
	v_cvt_pk_bf16_f32 v35, v35, v39
	ds_read2_b32 v[40:41], v5 offset0:16 offset1:49
	v_lshl_add_u64 v[44:45], v[42:43], 0, v[6:7]
	global_store_dwordx4 v[44:45], v[32:35], off
	s_waitcnt lgkmcnt(0)
	v_mul_f32_e32 v6, 0x3e16c740, v40
	v_mul_f32_e32 v32, 0x3e16c740, v41
	v_cvt_pk_bf16_f32 v32, v6, v32
	ds_read2_b32 v[34:35], v5 offset0:82 offset1:115
	s_waitcnt lgkmcnt(0)
	v_mul_f32_e32 v33, 0x3e16c740, v35
	v_mul_f32_e32 v6, 0x3e16c740, v34
	v_cvt_pk_bf16_f32 v33, v6, v33
	ds_read2_b32 v[34:35], v5 offset0:148 offset1:181
	s_waitcnt lgkmcnt(0)
	v_mul_f32_e32 v6, 0x3e16c740, v34
	v_mul_f32_e32 v34, 0x3e16c740, v35
	v_cvt_pk_bf16_f32 v34, v6, v34
	ds_read2_b32 v[40:41], v5 offset0:214 offset1:247
	v_cndmask_b32_e32 v6, v11, v37, vcc
	v_or_b32_e32 v6, s6, v6
	v_mul_u32_u24_e32 v6, 0x300, v6
	v_lshl_add_u64 v[44:45], v[42:43], 0, v[6:7]
	s_waitcnt lgkmcnt(0)
	v_mul_f32_e32 v35, 0x3e16c740, v40
	v_mul_f32_e32 v39, 0x3e16c740, v41
	v_cvt_pk_bf16_f32 v35, v35, v39
	ds_read2_b32 v[40:41], v5 offset0:24 offset1:57
	global_store_dwordx4 v[44:45], v[32:35], off
	s_waitcnt lgkmcnt(0)
	v_mul_f32_e32 v6, 0x3e16c740, v40
	v_mul_f32_e32 v32, 0x3e16c740, v41
	v_cvt_pk_bf16_f32 v32, v6, v32
	ds_read2_b32 v[34:35], v5 offset0:90 offset1:123
	s_waitcnt lgkmcnt(0)
	v_mul_f32_e32 v33, 0x3e16c740, v35
	v_mul_f32_e32 v6, 0x3e16c740, v34
	v_cvt_pk_bf16_f32 v33, v6, v33
	ds_read2_b32 v[34:35], v5 offset0:156 offset1:189
	s_waitcnt lgkmcnt(0)
	v_mul_f32_e32 v6, 0x3e16c740, v34
	v_mul_f32_e32 v34, 0x3e16c740, v35
	v_cvt_pk_bf16_f32 v34, v6, v34
	ds_read2_b32 v[40:41], v5 offset0:222 offset1:255
	v_cndmask_b32_e32 v6, v36, v38, vcc
	v_or_b32_e32 v6, s6, v6
	v_mul_u32_u24_e32 v6, 0x300, v6
	s_waitcnt lgkmcnt(0)
	v_mul_f32_e32 v35, 0x3e16c740, v40
	v_mul_f32_e32 v39, 0x3e16c740, v41
	v_lshl_add_u64 v[40:41], v[42:43], 0, v[6:7]
	v_cvt_pk_bf16_f32 v35, v35, v39
	global_store_dwordx4 v[40:41], v[32:35], off
	s_waitcnt lgkmcnt(0)

; #define LAS __attribute__((address_space(3)))
; __device__ __forceinline__ unsigned pkbf(float lo, float hi) { return pg8::cvt_pk_bf16(lo, hi); }
; #pragma unroll 8
;     for (int i = 0; i < 32; ++i) { const int kk = 2 * i + (lane >> 5); scr[kk * 33 + (lane & 31)] = W[(size_t)(k0 + kk) * N + n0 + (lane & 31)]; }
;     asm volatile("s_waitcnt lgkmcnt(0)" ::: "memory");
;     const int c = lane & 7;
; #pragma unroll
;     for (int j = 0; j < 4; ++j) { const int n = (lane >> 3) + 8 * j; const LAS float* s = scr + (8 * c) * 33 + n;
;         u32x4 o; o.x = pkbf(s[0 * 33] * sc, s[1 * 33] * sc); o.y = pkbf(s[2 * 33] * sc, s[3 * 33] * sc); o.z = pkbf(s[4 * 33] * sc, s[5 * 33] * sc); o.w = pkbf(s[6 * 33] * sc, s[7 * 33] * sc);
;         const int dn = ropeperm ? (n < 16 ? 2 * n : 2 * (n - 16) + 1) : n;
;         *(u32x4*)(WT + (size_t)(drow0 + dn) * ldk + kdst0 + k0 + 8 * c) = o; }
;     asm volatile("s_waitcnt lgkmcnt(0)" ::: "memory");
; __device__ __forceinline__ void prologue(const P& p, LAS unsigned char* lds, int gw, int NGW, int wave, int lane, int gtid, int GT, int which) {
;     ...
;         if (r < I_IN) { const int kb = r / 81, nb = r % 81, n0 = nb * 32; const int dr = n0 < 672 ? n0 : (n0 < 2208 ? 768 + (n0 - 672) : 2304 + (n0 - 2208));
.LBB0_42:
	s_lshl_b32 s14, s9, 1
	s_lshl_b32 s15, s10, 1
	v_or_b32_e32 v6, s14, v1
	v_or_b32_e32 v39, s15, v2
	s_add_i32 s16, s14, 4
	s_add_i32 s17, s15, 4
	s_add_i32 s20, s14, 8
	s_add_i32 s21, s15, 8
	s_add_i32 s24, s14, 12
	s_add_i32 s25, s15, 12
	s_add_i32 s26, s14, 16
	s_add_i32 s27, s15, 16
	s_add_i32 s28, s14, 20
	s_add_i32 s29, s15, 20
	s_add_i32 s30, s14, 24
	s_add_i32 s31, s15, 24
	s_add_i32 s14, s14, 28
	s_add_i32 s15, s15, 28
	v_add_u32_e32 v34, s6, v39
	v_or_b32_e32 v70, s16, v1
	v_or_b32_e32 v71, s17, v2
	v_or_b32_e32 v72, s20, v1
	v_or_b32_e32 v73, s21, v2
	v_or_b32_e32 v74, s24, v1
	v_or_b32_e32 v75, s25, v2
	v_or_b32_e32 v76, s26, v1
	v_or_b32_e32 v77, s27, v2
	v_or_b32_e32 v78, s28, v1
	v_or_b32_e32 v79, s29, v2
	v_or_b32_e32 v80, s30, v1
	v_or_b32_e32 v81, s31, v2
	v_or_b32_e32 v82, s14, v1
	v_or_b32_e32 v83, s15, v2
	v_add_u32_e32 v40, s0, v6
	v_mad_u64_u32 v[34:35], s[14:15], v34, s89, v[32:33]
	v_add_u32_e32 v44, s0, v70
	v_add_u32_e32 v42, s6, v71
	v_add_u32_e32 v48, s0, v72
	v_add_u32_e32 v46, s6, v73
	v_add_u32_e32 v52, s0, v74
	v_add_u32_e32 v50, s6, v75
	v_add_u32_e32 v56, s0, v76
	v_add_u32_e32 v54, s6, v77
	v_add_u32_e32 v60, s0, v78
	v_add_u32_e32 v58, s6, v79
	v_add_u32_e32 v64, s0, v80
	v_add_u32_e32 v62, s6, v81
	v_add_u32_e32 v68, s0, v82
	v_add_u32_e32 v66, s6, v83
	v_mad_u64_u32 v[40:41], s[14:15], v40, s89, v[32:33]
	v_mad_u64_u32 v[42:43], s[14:15], v42, s89, v[32:33]
	v_mad_u64_u32 v[44:45], s[14:15], v44, s89, v[32:33]
	v_mad_u64_u32 v[46:47], s[14:15], v46, s89, v[32:33]
	v_mad_u64_u32 v[48:49], s[14:15], v48, s89, v[32:33]
	v_mad_u64_u32 v[50:51], s[14:15], v50, s89, v[32:33]
	v_mad_u64_u32 v[52:53], s[14:15], v52, s89, v[32:33]
	v_mad_u64_u32 v[54:55], s[14:15], v54, s89, v[32:33]
	v_mad_u64_u32 v[56:57], s[14:15], v56, s89, v[32:33]
	v_mad_u64_u32 v[58:59], s[14:15], v58, s89, v[32:33]
	v_mad_u64_u32 v[60:61], s[14:15], v60, s89, v[32:33]
	v_mad_u64_u32 v[62:63], s[14:15], v62, s89, v[32:33]
	v_mad_u64_u32 v[64:65], s[14:15], v64, s89, v[32:33]
	v_mad_u64_u32 v[66:67], s[14:15], v66, s89, v[32:33]
	v_mad_u64_u32 v[68:69], s[14:15], v68, s89, v[32:33]
	global_load_dword v84, v[34:35], off nt
	global_load_dword v85, v[40:41], off nt
	global_load_dword v86, v[42:43], off nt
	global_load_dword v87, v[44:45], off nt
	global_load_dword v88, v[46:47], off nt
	global_load_dword v89, v[48:49], off nt
	global_load_dword v90, v[50:51], off nt
	global_load_dword v91, v[52:53], off nt
	global_load_dword v92, v[54:55], off nt
	global_load_dword v93, v[56:57], off nt
	global_load_dword v94, v[58:59], off nt
	global_load_dword v95, v[60:61], off nt
	global_load_dword v96, v[62:63], off nt
	global_load_dword v97, v[64:65], off nt
	global_load_dword v98, v[66:67], off nt
	global_load_dword v99, v[68:69], off nt
	s_add_i32 s10, s10, 16
	s_add_i32 s9, s9, 16
	s_add_i32 s11, s11, -16
	v_mad_u64_u32 v[34:35], s[14:15], v39, s3, v[8:9]
	s_cmp_lg_u32 s11, 0
	v_mad_u64_u32 v[40:41], s[14:15], v6, s3, v[8:9]
	v_mad_u64_u32 v[42:43], s[14:15], v71, s3, v[8:9]
	v_mad_u64_u32 v[44:45], s[14:15], v70, s3, v[8:9]
	v_mad_u64_u32 v[46:47], s[14:15], v73, s3, v[8:9]
	v_mad_u64_u32 v[48:49], s[14:15], v72, s3, v[8:9]
	v_mad_u64_u32 v[50:51], s[14:15], v75, s3, v[8:9]
	v_mad_u64_u32 v[52:53], s[14:15], v74, s3, v[8:9]
	v_mad_u64_u32 v[54:55], s[14:15], v77, s3, v[8:9]
	v_mad_u64_u32 v[56:57], s[14:15], v76, s3, v[8:9]
	v_mad_u64_u32 v[58:59], s[14:15], v79, s3, v[8:9]
	v_mad_u64_u32 v[60:61], s[14:15], v78, s3, v[8:9]
	v_mad_u64_u32 v[62:63], s[14:15], v81, s3, v[8:9]
	v_mad_u64_u32 v[64:65], s[14:15], v80, s3, v[8:9]
	v_mad_u64_u32 v[66:67], s[14:15], v83, s3, v[8:9]
	v_mad_u64_u32 v[68:69], s[14:15], v82, s3, v[8:9]
	s_waitcnt vmcnt(15)
	ds_write_b32 v34, v84
	s_waitcnt vmcnt(14)
	ds_write_b32 v40, v85
	s_waitcnt vmcnt(13)
	ds_write_b32 v42, v86
	s_waitcnt vmcnt(12)
	ds_write_b32 v44, v87
	s_waitcnt vmcnt(11)
	ds_write_b32 v46, v88
	s_waitcnt vmcnt(10)
	ds_write_b32 v48, v89
	s_waitcnt vmcnt(9)
	ds_write_b32 v50, v90
	s_waitcnt vmcnt(8)
	ds_write_b32 v52, v91
	s_waitcnt vmcnt(7)
	ds_write_b32 v54, v92
	s_waitcnt vmcnt(6)
	ds_write_b32 v56, v93
	s_waitcnt vmcnt(5)
	ds_write_b32 v58, v94
	s_waitcnt vmcnt(4)
	ds_write_b32 v60, v95
	s_waitcnt vmcnt(3)
	ds_write_b32 v62, v96
	s_waitcnt vmcnt(2)
	ds_write_b32 v64, v97
	s_waitcnt vmcnt(1)
	ds_write_b32 v66, v98
	s_waitcnt vmcnt(0)
	ds_write_b32 v68, v99
	s_cbranch_scc1 .LBB0_42
	s_and_b32 s0, 0xffff, s8
	s_and_b32 s7, 0xffff, s7
	s_add_i32 s8, s0, 0x60
	s_waitcnt lgkmcnt(0)
	s_cmp_lt_u32 s7, 21
	ds_read2_b32 v[32:33], v5 offset1:33
	s_cselect_b32 s7, s0, s8
	s_and_b32 s0, 0xffff, s6
	s_waitcnt lgkmcnt(0)
	v_cvt_pk_bf16_f32 v32, v32, v33
	ds_read2_b32 v[34:35], v5 offset0:66 offset1:99
	s_lshl_b32 s0, s0, 1
	v_or_b32_e32 v6, s7, v3
	s_waitcnt lgkmcnt(0)
	v_cvt_pk_bf16_f32 v33, v34, v35
	ds_read2_b32 v[34:35], v5 offset0:132 offset1:165
	v_lshl_add_u64 v[42:43], v[20:21], 0, s[0:1]
	v_lshlrev_b32_e32 v6, 11, v6
	s_waitcnt lgkmcnt(0)
	v_cvt_pk_bf16_f32 v34, v34, v35
	ds_read2_b32 v[40:41], v5 offset0:198 offset1:231
	s_waitcnt lgkmcnt(0)
	v_cvt_pk_bf16_f32 v35, v40, v41
	v_lshl_add_u64 v[44:45], v[42:43], 0, v[6:7]
	ds_read2_b32 v[40:41], v5 offset0:8 offset1:41
	global_store_dwordx4 v[44:45], v[32:35], off
	v_or_b32_e32 v6, s7, v9
	v_lshlrev_b32_e32 v6, 11, v6
	s_waitcnt lgkmcnt(0)
	v_cvt_pk_bf16_f32 v32, v40, v41
	ds_read2_b32 v[34:35], v5 offset0:74 offset1:107
	s_waitcnt lgkmcnt(0)
	v_cvt_pk_bf16_f32 v33, v34, v35
	ds_read2_b32 v[34:35], v5 offset0:140 offset1:173
	s_waitcnt lgkmcnt(0)
	v_cvt_pk_bf16_f32 v34, v34, v35
	ds_read2_b32 v[40:41], v5 offset0:206 offset1:239
	s_waitcnt lgkmcnt(0)
	v_cvt_pk_bf16_f32 v35, v40, v41
	v_lshl_add_u64 v[44:45], v[42:43], 0, v[6:7]
	ds_read2_b32 v[40:41], v5 offset0:16 offset1:49
	global_store_dwordx4 v[44:45], v[32:35], off
	v_or_b32_e32 v6, s7, v11
	v_lshlrev_b32_e32 v6, 11, v6
	s_waitcnt lgkmcnt(0)
	v_cvt_pk_bf16_f32 v32, v40, v41
	ds_read2_b32 v[34:35], v5 offset0:82 offset1:115
	s_waitcnt lgkmcnt(0)
	v_cvt_pk_bf16_f32 v33, v34, v35
	ds_read2_b32 v[34:35], v5 offset0:148 offset1:181
	s_waitcnt lgkmcnt(0)
	v_cvt_pk_bf16_f32 v34, v34, v35
	ds_read2_b32 v[40:41], v5 offset0:214 offset1:247
	s_waitcnt lgkmcnt(0)
	v_cvt_pk_bf16_f32 v35, v40, v41
	v_lshl_add_u64 v[44:45], v[42:43], 0, v[6:7]
	ds_read2_b32 v[40:41], v5 offset0:24 offset1:57
	global_store_dwordx4 v[44:45], v[32:35], off
	v_or_b32_e32 v6, s7, v36
	v_lshlrev_b32_e32 v6, 11, v6
	s_waitcnt lgkmcnt(0)
	v_cvt_pk_bf16_f32 v32, v40, v41
	ds_read2_b32 v[34:35], v5 offset0:90 offset1:123
	s_waitcnt lgkmcnt(0)
	v_cvt_pk_bf16_f32 v33, v34, v35
	ds_read2_b32 v[34:35], v5 offset0:156 offset1:189
	s_waitcnt lgkmcnt(0)
	v_cvt_pk_bf16_f32 v34, v34, v35
	ds_read2_b32 v[40:41], v5 offset0:222 offset1:255
	s_waitcnt lgkmcnt(0)
	v_cvt_pk_bf16_f32 v35, v40, v41
	v_lshl_add_u64 v[40:41], v[42:43], 0, v[6:7]
	global_store_dwordx4 v[40:41], v[32:35], off
	s_waitcnt lgkmcnt(0)

; #pragma unroll 8
;     for (int i = 0; i < 32; ++i) { const int kk = 2 * i + (lane >> 5); scr[kk * 33 + (lane & 31)] = W[(size_t)(k0 + kk) * N + n0 + (lane & 31)]; }
.LBB0_49:
	s_lshl_b32 s16, s9, 1
	s_lshl_b32 s17, s14, 1
	v_or_b32_e32 v39, s16, v1
	v_or_b32_e32 v70, s17, v2
	s_add_i32 s20, s16, 4
	s_add_i32 s21, s17, 4
	s_add_i32 s24, s16, 8
	s_add_i32 s25, s17, 8
	s_add_i32 s26, s16, 12
	s_add_i32 s27, s17, 12
	s_add_i32 s28, s16, 16
	s_add_i32 s29, s17, 16
	s_add_i32 s30, s16, 20
	s_add_i32 s31, s17, 20
	s_add_i32 s68, s16, 24
	s_add_i32 s69, s17, 24
	s_add_i32 s16, s16, 28
	s_add_i32 s17, s17, 28
	v_add_u32_e32 v40, s8, v70
	v_or_b32_e32 v71, s20, v1
	v_or_b32_e32 v72, s21, v2
	v_or_b32_e32 v73, s24, v1
	v_or_b32_e32 v74, s25, v2
	v_or_b32_e32 v75, s26, v1
	v_or_b32_e32 v76, s27, v2
	v_or_b32_e32 v77, s28, v1
	v_or_b32_e32 v78, s29, v2
	v_or_b32_e32 v79, s30, v1
	v_or_b32_e32 v80, s31, v2
	v_or_b32_e32 v81, s68, v1
	v_or_b32_e32 v82, s69, v2
	v_or_b32_e32 v83, s16, v1
	v_or_b32_e32 v84, s17, v2
	v_add_u32_e32 v34, s11, v39
	v_ashrrev_i32_e32 v41, 31, v40
	v_add_u32_e32 v42, s11, v71
	v_add_u32_e32 v44, s8, v72
	v_add_u32_e32 v46, s11, v73
	v_add_u32_e32 v48, s8, v74
	v_add_u32_e32 v50, s11, v75
	v_add_u32_e32 v52, s8, v76
	v_add_u32_e32 v54, s11, v77
	v_add_u32_e32 v56, s8, v78
	v_add_u32_e32 v58, s11, v79
	v_add_u32_e32 v60, s8, v80
	v_add_u32_e32 v62, s11, v81
	v_add_u32_e32 v64, s8, v82
	v_add_u32_e32 v66, s11, v83
	v_add_u32_e32 v68, s8, v84
	v_ashrrev_i32_e32 v35, 31, v34
	v_lshlrev_b64 v[40:41], 12, v[40:41]
	v_ashrrev_i32_e32 v45, 31, v44
	v_ashrrev_i32_e32 v43, 31, v42
	v_ashrrev_i32_e32 v49, 31, v48
	v_ashrrev_i32_e32 v47, 31, v46
	v_ashrrev_i32_e32 v53, 31, v52
	v_ashrrev_i32_e32 v51, 31, v50
	v_ashrrev_i32_e32 v57, 31, v56
	v_ashrrev_i32_e32 v55, 31, v54
	v_ashrrev_i32_e32 v61, 31, v60
	v_ashrrev_i32_e32 v59, 31, v58
	v_ashrrev_i32_e32 v65, 31, v64
	v_ashrrev_i32_e32 v63, 31, v62
	v_ashrrev_i32_e32 v69, 31, v68
	v_ashrrev_i32_e32 v67, 31, v66
	v_lshlrev_b64 v[34:35], 12, v[34:35]
	v_lshl_add_u64 v[40:41], v[32:33], 0, v[40:41]
	v_lshlrev_b64 v[42:43], 12, v[42:43]
	v_lshlrev_b64 v[44:45], 12, v[44:45]
	v_lshlrev_b64 v[46:47], 12, v[46:47]
	v_lshlrev_b64 v[48:49], 12, v[48:49]
	v_lshlrev_b64 v[50:51], 12, v[50:51]
	v_lshlrev_b64 v[52:53], 12, v[52:53]
	v_lshlrev_b64 v[54:55], 12, v[54:55]
	v_lshlrev_b64 v[56:57], 12, v[56:57]
	v_lshlrev_b64 v[58:59], 12, v[58:59]
	v_lshlrev_b64 v[60:61], 12, v[60:61]
	v_lshlrev_b64 v[62:63], 12, v[62:63]
	v_lshlrev_b64 v[64:65], 12, v[64:65]
	v_lshlrev_b64 v[66:67], 12, v[66:67]
	v_lshlrev_b64 v[68:69], 12, v[68:69]
	v_lshl_add_u64 v[34:35], v[32:33], 0, v[34:35]
	v_lshl_add_u64 v[44:45], v[32:33], 0, v[44:45]
	v_lshl_add_u64 v[42:43], v[32:33], 0, v[42:43]
	v_lshl_add_u64 v[48:49], v[32:33], 0, v[48:49]
	v_lshl_add_u64 v[46:47], v[32:33], 0, v[46:47]
	v_lshl_add_u64 v[52:53], v[32:33], 0, v[52:53]
	v_lshl_add_u64 v[50:51], v[32:33], 0, v[50:51]
	v_lshl_add_u64 v[56:57], v[32:33], 0, v[56:57]
	v_lshl_add_u64 v[54:55], v[32:33], 0, v[54:55]
	v_lshl_add_u64 v[60:61], v[32:33], 0, v[60:61]
	v_lshl_add_u64 v[58:59], v[32:33], 0, v[58:59]
	v_lshl_add_u64 v[64:65], v[32:33], 0, v[64:65]
	v_lshl_add_u64 v[62:63], v[32:33], 0, v[62:63]
	v_lshl_add_u64 v[68:69], v[32:33], 0, v[68:69]
	v_lshl_add_u64 v[66:67], v[32:33], 0, v[66:67]
	global_load_dword v85, v[40:41], off nt
	global_load_dword v86, v[34:35], off nt
	global_load_dword v87, v[44:45], off nt
	global_load_dword v88, v[42:43], off nt
	global_load_dword v89, v[48:49], off nt
	global_load_dword v90, v[46:47], off nt
	global_load_dword v91, v[52:53], off nt
	global_load_dword v92, v[50:51], off nt
	global_load_dword v93, v[56:57], off nt
	global_load_dword v94, v[54:55], off nt
	global_load_dword v95, v[60:61], off nt
	global_load_dword v96, v[58:59], off nt
	global_load_dword v97, v[64:65], off nt
	global_load_dword v98, v[62:63], off nt
	global_load_dword v99, v[68:69], off nt
	global_load_dword v100, v[66:67], off nt
	s_add_i32 s14, s14, 16
	s_add_i32 s9, s9, 16
	s_add_i32 s15, s15, -16
	v_mad_u64_u32 v[34:35], s[16:17], v70, s3, v[8:9]
	s_cmp_lg_u32 s15, 0
	v_mad_u64_u32 v[40:41], s[16:17], v39, s3, v[8:9]
	v_mad_u64_u32 v[42:43], s[16:17], v72, s3, v[8:9]
	v_mad_u64_u32 v[44:45], s[16:17], v71, s3, v[8:9]
	v_mad_u64_u32 v[46:47], s[16:17], v74, s3, v[8:9]
	v_mad_u64_u32 v[48:49], s[16:17], v73, s3, v[8:9]
	v_mad_u64_u32 v[50:51], s[16:17], v76, s3, v[8:9]
	v_mad_u64_u32 v[52:53], s[16:17], v75, s3, v[8:9]
	v_mad_u64_u32 v[54:55], s[16:17], v78, s3, v[8:9]
	v_mad_u64_u32 v[56:57], s[16:17], v77, s3, v[8:9]
	v_mad_u64_u32 v[58:59], s[16:17], v80, s3, v[8:9]
	v_mad_u64_u32 v[60:61], s[16:17], v79, s3, v[8:9]
	v_mad_u64_u32 v[62:63], s[16:17], v82, s3, v[8:9]
	v_mad_u64_u32 v[64:65], s[16:17], v81, s3, v[8:9]
	v_mad_u64_u32 v[66:67], s[16:17], v84, s3, v[8:9]
	v_mad_u64_u32 v[68:69], s[16:17], v83, s3, v[8:9]
	s_waitcnt vmcnt(15)
	ds_write_b32 v34, v85
	s_waitcnt vmcnt(14)
	ds_write_b32 v40, v86
	s_waitcnt vmcnt(13)
	ds_write_b32 v42, v87
	s_waitcnt vmcnt(12)
	ds_write_b32 v44, v88
	s_waitcnt vmcnt(11)
	ds_write_b32 v46, v89
	s_waitcnt vmcnt(10)
	ds_write_b32 v48, v90
	s_waitcnt vmcnt(9)
	ds_write_b32 v50, v91
	s_waitcnt vmcnt(8)
	ds_write_b32 v52, v92
	s_waitcnt vmcnt(7)
	ds_write_b32 v54, v93
	s_waitcnt vmcnt(6)
	ds_write_b32 v56, v94
	s_waitcnt vmcnt(5)
	ds_write_b32 v58, v95
	s_waitcnt vmcnt(4)
	ds_write_b32 v60, v96
	s_waitcnt vmcnt(3)
	ds_write_b32 v62, v97
	s_waitcnt vmcnt(2)
	ds_write_b32 v64, v98
	s_waitcnt vmcnt(1)
	ds_write_b32 v66, v99
	s_waitcnt vmcnt(0)
	ds_write_b32 v68, v100
	s_cbranch_scc1 .LBB0_49
; #define LAS __attribute__((address_space(3)))
; __device__ __forceinline__ unsigned pkbf(float lo, float hi) { return pg8::cvt_pk_bf16(lo, hi); }
;     ...
;     asm volatile("s_waitcnt lgkmcnt(0)" ::: "memory");
;     const int c = lane & 7;
; #pragma unroll
;     for (int j = 0; j < 4; ++j) { const int n = (lane >> 3) + 8 * j; const LAS float* s = scr + (8 * c) * 33 + n;
;         u32x4 o; o.x = pkbf(s[0 * 33] * sc, s[1 * 33] * sc); o.y = pkbf(s[2 * 33] * sc, s[3 * 33] * sc); o.z = pkbf(s[4 * 33] * sc, s[5 * 33] * sc); o.w = pkbf(s[6 * 33] * sc, s[7 * 33] * sc);
;         const int dn = ropeperm ? (n < 16 ? 2 * n : 2 * (n - 16) + 1) : n;
;         *(u32x4*)(WT + (size_t)(drow0 + dn) * ldk + kdst0 + k0 + 8 * c) = o; }
;     asm volatile("s_waitcnt lgkmcnt(0)" ::: "memory");
; __device__ __forceinline__ void prologue(const P& p, LAS unsigned char* lds, int gw, int NGW, int wave, int lane, int gtid, int GT, int which) {
;     ...
;             else { r -= 2 * I_G; const int kb = r / 32, nb = r % 32; transpose_item(wd, DM, kb * 64, nb * 32, WD, DFF, 0, nb * 32, false, scr, lane); }
	s_and_b64 s[14:15], s[6:7], exec
	s_mov_b32 s9, 0x2080000
	s_cselect_b32 s9, s9, 0x1000000
	s_add_u32 s11, s50, s9
	s_addc_u32 s14, s51, 0
	s_ashr_i32 s9, s8, 31
	s_waitcnt lgkmcnt(0)
	s_lshl_b64 s[8:9], s[8:9], 1
	ds_read2_b32 v[32:33], v5 offset1:33
	v_or_b32_e32 v39, s10, v3
	s_add_u32 s8, s11, s8
	v_lshlrev_b32_e32 v40, 1, v10
	s_waitcnt lgkmcnt(0)
	v_cvt_pk_bf16_f32 v32, v32, v33
	ds_read2_b32 v[34:35], v5 offset0:66 offset1:99
	v_mov_b32_e32 v41, v7
	v_mul_u32_u24_e32 v39, 0xb00, v39
	s_addc_u32 s9, s14, s9
	s_waitcnt lgkmcnt(0)
	v_cvt_pk_bf16_f32 v33, v34, v35
	ds_read2_b32 v[34:35], v5 offset0:132 offset1:165
	v_lshl_add_u64 v[40:41], s[8:9], 0, v[40:41]
	v_lshlrev_b32_e32 v44, 1, v39
	v_mov_b32_e32 v45, v7
	s_waitcnt lgkmcnt(0)
	v_cvt_pk_bf16_f32 v34, v34, v35
	ds_read2_b32 v[42:43], v5 offset0:198 offset1:231
	s_waitcnt lgkmcnt(0)
	v_cvt_pk_bf16_f32 v35, v42, v43
	v_lshl_add_u64 v[44:45], v[40:41], 0, v[44:45]
	v_or_b32_e32 v39, s10, v9
	ds_read2_b32 v[42:43], v5 offset0:8 offset1:41
	global_store_dwordx4 v[44:45], v[32:35], off
	v_mul_u32_u24_e32 v39, 0xb00, v39
	v_mov_b32_e32 v45, v7
	s_waitcnt lgkmcnt(0)
	v_cvt_pk_bf16_f32 v32, v42, v43
	ds_read2_b32 v[34:35], v5 offset0:74 offset1:107
	s_waitcnt lgkmcnt(0)
	v_cvt_pk_bf16_f32 v33, v34, v35
	ds_read2_b32 v[34:35], v5 offset0:140 offset1:173
	v_lshlrev_b32_e32 v44, 1, v39
	s_waitcnt lgkmcnt(0)
	v_cvt_pk_bf16_f32 v34, v34, v35
	ds_read2_b32 v[42:43], v5 offset0:206 offset1:239
	s_waitcnt lgkmcnt(0)
	v_cvt_pk_bf16_f32 v35, v42, v43
	v_lshl_add_u64 v[44:45], v[40:41], 0, v[44:45]
	v_or_b32_e32 v39, s10, v11
	ds_read2_b32 v[42:43], v5 offset0:16 offset1:49
	global_store_dwordx4 v[44:45], v[32:35], off
	v_mul_u32_u24_e32 v39, 0xb00, v39
	v_mov_b32_e32 v45, v7
	s_waitcnt lgkmcnt(0)
	v_cvt_pk_bf16_f32 v32, v42, v43
	ds_read2_b32 v[34:35], v5 offset0:82 offset1:115
	s_waitcnt lgkmcnt(0)
	v_cvt_pk_bf16_f32 v33, v34, v35
	ds_read2_b32 v[34:35], v5 offset0:148 offset1:181
	v_lshlrev_b32_e32 v44, 1, v39
	s_waitcnt lgkmcnt(0)
	v_cvt_pk_bf16_f32 v34, v34, v35
	ds_read2_b32 v[42:43], v5 offset0:214 offset1:247
	s_waitcnt lgkmcnt(0)
	v_cvt_pk_bf16_f32 v35, v42, v43
	v_lshl_add_u64 v[44:45], v[40:41], 0, v[44:45]
	ds_read2_b32 v[42:43], v5 offset0:24 offset1:57
	global_store_dwordx4 v[44:45], v[32:35], off
	v_mov_b32_e32 v45, v7
	s_mov_b64 s[8:9], 0
	s_waitcnt lgkmcnt(0)
	v_cvt_pk_bf16_f32 v32, v42, v43
	ds_read2_b32 v[34:35], v5 offset0:90 offset1:123
	s_waitcnt lgkmcnt(0)
	v_cvt_pk_bf16_f32 v33, v34, v35
	ds_read2_b32 v[34:35], v5 offset0:156 offset1:189
	s_waitcnt lgkmcnt(0)
	v_cvt_pk_bf16_f32 v34, v34, v35
	v_or_b32_e32 v35, s10, v36
	v_mul_u32_u24_e32 v35, 0xb00, v35
	v_lshlrev_b32_e32 v44, 1, v35
	v_lshl_add_u64 v[40:41], v[40:41], 0, v[44:45]
	ds_read2_b32 v[42:43], v5 offset0:222 offset1:255
	s_waitcnt lgkmcnt(0)
	v_cvt_pk_bf16_f32 v35, v42, v43
	global_store_dwordx4 v[40:41], v[32:35], off
	s_waitcnt lgkmcnt(0)

; #pragma unroll 8
;     for (int i = 0; i < 32; ++i) { const int kk = 2 * i + (lane >> 5); scr[kk * 33 + (lane & 31)] = W[(size_t)(k0 + kk) * N + n0 + (lane & 31)]; }
; __device__ __forceinline__ void prologue(const P& p, LAS unsigned char* lds, int gw, int NGW, int wave, int lane, int gtid, int GT, int which) {
;     ...
;             if (r < 2 * I_G) { const bool up = r >= I_G; const int q = up ? r - I_G : r; const int kb = q / 88, nb = q % 88, n0 = nb * 32;
;                 transpose_item(up ? wu : wg, DFF, kb * 64, n0, WGU, DM, 0, (n0 >> 7) * 256 + (n0 & 127) + (up ? 128 : 0), false, scr, lane); }
.LBB0_53:
	s_lshl_b32 s20, s15, 1
	s_lshl_b32 s21, s16, 1
	v_or_b32_e32 v6, s20, v1
	v_or_b32_e32 v39, s21, v2
	s_add_i32 s24, s20, 4
	s_add_i32 s25, s21, 4
	s_add_i32 s26, s20, 8
	s_add_i32 s27, s21, 8
	s_add_i32 s28, s20, 12
	s_add_i32 s29, s21, 12
	s_add_i32 s30, s20, 16
	s_add_i32 s31, s21, 16
	s_add_i32 s68, s20, 20
	s_add_i32 s69, s21, 20
	s_add_i32 s70, s20, 24
	s_add_i32 s71, s21, 24
	s_add_i32 s20, s20, 28
	s_add_i32 s21, s21, 28
	v_add_u32_e32 v34, s8, v39
	v_or_b32_e32 v70, s24, v1
	v_or_b32_e32 v71, s25, v2
	v_or_b32_e32 v72, s26, v1
	v_or_b32_e32 v73, s27, v2
	v_or_b32_e32 v74, s28, v1
	v_or_b32_e32 v75, s29, v2
	v_or_b32_e32 v76, s30, v1
	v_or_b32_e32 v77, s31, v2
	v_or_b32_e32 v78, s68, v1
	v_or_b32_e32 v79, s69, v2
	v_or_b32_e32 v80, s70, v1
	v_or_b32_e32 v81, s71, v2
	v_or_b32_e32 v82, s20, v1
	v_or_b32_e32 v83, s21, v2
	v_add_u32_e32 v40, s9, v6
	v_mad_i64_i32 v[34:35], s[20:21], v34, s66, v[32:33]
	v_add_u32_e32 v44, s9, v70
	v_add_u32_e32 v42, s8, v71
	v_add_u32_e32 v48, s9, v72
	v_add_u32_e32 v46, s8, v73
	v_add_u32_e32 v52, s9, v74
	v_add_u32_e32 v50, s8, v75
	v_add_u32_e32 v56, s9, v76
	v_add_u32_e32 v54, s8, v77
	v_add_u32_e32 v60, s9, v78
	v_add_u32_e32 v58, s8, v79
	v_add_u32_e32 v64, s9, v80
	v_add_u32_e32 v62, s8, v81
	v_add_u32_e32 v68, s9, v82
	v_add_u32_e32 v66, s8, v83
	v_mad_i64_i32 v[40:41], s[20:21], v40, s66, v[32:33]
	v_mad_i64_i32 v[42:43], s[20:21], v42, s66, v[32:33]
	v_mad_i64_i32 v[44:45], s[20:21], v44, s66, v[32:33]
	v_mad_i64_i32 v[46:47], s[20:21], v46, s66, v[32:33]
	v_mad_i64_i32 v[48:49], s[20:21], v48, s66, v[32:33]
	v_mad_i64_i32 v[50:51], s[20:21], v50, s66, v[32:33]
	v_mad_i64_i32 v[52:53], s[20:21], v52, s66, v[32:33]
	v_mad_i64_i32 v[54:55], s[20:21], v54, s66, v[32:33]
	v_mad_i64_i32 v[56:57], s[20:21], v56, s66, v[32:33]
	v_mad_i64_i32 v[58:59], s[20:21], v58, s66, v[32:33]
	v_mad_i64_i32 v[60:61], s[20:21], v60, s66, v[32:33]
	v_mad_i64_i32 v[62:63], s[20:21], v62, s66, v[32:33]
	v_mad_i64_i32 v[64:65], s[20:21], v64, s66, v[32:33]
	v_mad_i64_i32 v[66:67], s[20:21], v66, s66, v[32:33]
	v_mad_i64_i32 v[68:69], s[20:21], v68, s66, v[32:33]
	global_load_dword v84, v[34:35], off nt
	global_load_dword v85, v[40:41], off nt
	global_load_dword v86, v[42:43], off nt
	global_load_dword v87, v[44:45], off nt
	global_load_dword v88, v[46:47], off nt
	global_load_dword v89, v[48:49], off nt
	global_load_dword v90, v[50:51], off nt
	global_load_dword v91, v[52:53], off nt
	global_load_dword v92, v[54:55], off nt
	global_load_dword v93, v[56:57], off nt
	global_load_dword v94, v[58:59], off nt
	global_load_dword v95, v[60:61], off nt
	global_load_dword v96, v[62:63], off nt
	global_load_dword v97, v[64:65], off nt
	global_load_dword v98, v[66:67], off nt
	global_load_dword v99, v[68:69], off nt
	s_add_i32 s16, s16, 16
	s_add_i32 s15, s15, 16
	s_add_i32 s17, s17, -16
	v_mad_u64_u32 v[34:35], s[20:21], v39, s3, v[8:9]
	s_cmp_lg_u32 s17, 0
	v_mad_u64_u32 v[40:41], s[20:21], v6, s3, v[8:9]
	v_mad_u64_u32 v[42:43], s[20:21], v71, s3, v[8:9]
	v_mad_u64_u32 v[44:45], s[20:21], v70, s3, v[8:9]
	v_mad_u64_u32 v[46:47], s[20:21], v73, s3, v[8:9]
	v_mad_u64_u32 v[48:49], s[20:21], v72, s3, v[8:9]
	v_mad_u64_u32 v[50:51], s[20:21], v75, s3, v[8:9]
	v_mad_u64_u32 v[52:53], s[20:21], v74, s3, v[8:9]
	v_mad_u64_u32 v[54:55], s[20:21], v77, s3, v[8:9]
	v_mad_u64_u32 v[56:57], s[20:21], v76, s3, v[8:9]
	v_mad_u64_u32 v[58:59], s[20:21], v79, s3, v[8:9]
	v_mad_u64_u32 v[60:61], s[20:21], v78, s3, v[8:9]
	v_mad_u64_u32 v[62:63], s[20:21], v81, s3, v[8:9]
	v_mad_u64_u32 v[64:65], s[20:21], v80, s3, v[8:9]
	v_mad_u64_u32 v[66:67], s[20:21], v83, s3, v[8:9]
	v_mad_u64_u32 v[68:69], s[20:21], v82, s3, v[8:9]
	s_waitcnt vmcnt(15)
	ds_write_b32 v34, v84
	s_waitcnt vmcnt(14)
	ds_write_b32 v40, v85
	s_waitcnt vmcnt(13)
	ds_write_b32 v42, v86
	s_waitcnt vmcnt(12)
	ds_write_b32 v44, v87
	s_waitcnt vmcnt(11)
	ds_write_b32 v46, v88
	s_waitcnt vmcnt(10)
	ds_write_b32 v48, v89
	s_waitcnt vmcnt(9)
	ds_write_b32 v50, v90
	s_waitcnt vmcnt(8)
	ds_write_b32 v52, v91
	s_waitcnt vmcnt(7)
	ds_write_b32 v54, v92
	s_waitcnt vmcnt(6)
	ds_write_b32 v56, v93
	s_waitcnt vmcnt(5)
	ds_write_b32 v58, v94
	s_waitcnt vmcnt(4)
	ds_write_b32 v60, v95
	s_waitcnt vmcnt(3)
	ds_write_b32 v62, v96
	s_waitcnt vmcnt(2)
	ds_write_b32 v64, v97
	s_waitcnt vmcnt(1)
	ds_write_b32 v66, v98
	s_waitcnt vmcnt(0)
	ds_write_b32 v68, v99
	s_cbranch_scc1 .LBB0_53
; #define LAS __attribute__((address_space(3)))
; __device__ __forceinline__ unsigned pkbf(float lo, float hi) { return pg8::cvt_pk_bf16(lo, hi); }
;     ...
;     asm volatile("s_waitcnt lgkmcnt(0)" ::: "memory");
;     const int c = lane & 7;
; #pragma unroll
;     for (int j = 0; j < 4; ++j) { const int n = (lane >> 3) + 8 * j; const LAS float* s = scr + (8 * c) * 33 + n;
;         u32x4 o; o.x = pkbf(s[0 * 33] * sc, s[1 * 33] * sc); o.y = pkbf(s[2 * 33] * sc, s[3 * 33] * sc); o.z = pkbf(s[4 * 33] * sc, s[5 * 33] * sc); o.w = pkbf(s[6 * 33] * sc, s[7 * 33] * sc);
;         const int dn = ropeperm ? (n < 16 ? 2 * n : 2 * (n - 16) + 1) : n;
;         *(u32x4*)(WT + (size_t)(drow0 + dn) * ldk + kdst0 + k0 + 8 * c) = o; }
;     asm volatile("s_waitcnt lgkmcnt(0)" ::: "memory");
; __device__ __forceinline__ void prologue(const P& p, LAS unsigned char* lds, int gw, int NGW, int wave, int lane, int gtid, int GT, int which) {
;     ...
;             bf16_t* WGU = (bf16_t*)(ws + (f ? WS_WGU2 : WS_WGU1)); bf16_t* WD = (bf16_t*)(ws + (f ? WS_WD2 : WS_WD1));
;             const float* wg = p.in[f ? 26 : 3]; const float* wu = p.in[f ? 27 : 4]; const float* wd = p.in[f ? 28 : 5];
;             if (r < 2 * I_G) { const bool up = r >= I_G; const int q = up ? r - I_G : r; const int kb = q / 88, nb = q % 88, n0 = nb * 32;
;                 transpose_item(up ? wu : wg, DFF, kb * 64, n0, WGU, DM, 0, (n0 >> 7) * 256 + (n0 & 127) + (up ? 128 : 0), false, scr, lane); }
	s_lshl_b32 s0, s0, 6
	s_and_b64 s[10:11], s[10:11], exec
	s_cselect_b32 s9, 0x80, 0
	s_and_b64 s[6:7], s[6:7], exec
	s_mov_b32 s6, 0x1580000
	s_waitcnt lgkmcnt(0)
	s_cselect_b32 s6, s6, 0x500000
	s_and_b32 s7, s14, 0x60
	ds_read2_b32 v[32:33], v5 offset1:33
	s_or_b32 s7, s7, s9
	s_waitcnt lgkmcnt(0)
	v_cvt_pk_bf16_f32 v32, v32, v33
	ds_read2_b32 v[34:35], v5 offset0:66 offset1:99
	s_add_u32 s10, s50, s6
	s_addc_u32 s11, s51, 0
	s_waitcnt lgkmcnt(0)
	v_cvt_pk_bf16_f32 v33, v34, v35
	ds_read2_b32 v[34:35], v5 offset0:132 offset1:165
	s_and_b32 s0, s0, 0xffffff00
	s_ashr_i32 s9, s8, 31
	s_or_b32 s0, s7, s0
	s_lshl_b64 s[6:7], s[8:9], 1
	s_waitcnt lgkmcnt(0)
	v_cvt_pk_bf16_f32 v34, v34, v35
	ds_read2_b32 v[40:41], v5 offset0:198 offset1:231
	s_add_u32 s6, s10, s6
	s_waitcnt lgkmcnt(0)
	v_cvt_pk_bf16_f32 v35, v40, v41
	v_or_b32_e32 v40, s0, v3
	s_addc_u32 s7, s11, s7
	v_lshlrev_b32_e32 v6, 1, v10
	v_ashrrev_i32_e32 v41, 31, v40
	v_lshl_add_u64 v[42:43], s[6:7], 0, v[6:7]
	v_lshlrev_b64 v[40:41], 11, v[40:41]
	ds_read2_b32 v[44:45], v5 offset0:8 offset1:41
	v_lshl_add_u64 v[40:41], v[42:43], 0, v[40:41]
	global_store_dwordx4 v[40:41], v[32:35], off
	s_waitcnt lgkmcnt(0)
	s_nop 0
	v_cvt_pk_bf16_f32 v32, v44, v45
	v_or_b32_e32 v44, s0, v9
	v_ashrrev_i32_e32 v45, 31, v44
	ds_read2_b32 v[34:35], v5 offset0:74 offset1:107
	v_lshlrev_b64 v[44:45], 11, v[44:45]
	s_waitcnt lgkmcnt(0)
	v_cvt_pk_bf16_f32 v33, v34, v35
	ds_read2_b32 v[34:35], v5 offset0:140 offset1:173
	v_lshl_add_u64 v[44:45], v[42:43], 0, v[44:45]
	s_waitcnt lgkmcnt(0)
	v_cvt_pk_bf16_f32 v34, v34, v35
	ds_read2_b32 v[40:41], v5 offset0:206 offset1:239
	s_waitcnt lgkmcnt(0)
	v_cvt_pk_bf16_f32 v35, v40, v41
	global_store_dwordx4 v[44:45], v[32:35], off
	v_or_b32_e32 v44, s0, v11
	ds_read2_b32 v[40:41], v5 offset0:16 offset1:49
	s_waitcnt lgkmcnt(0)
	v_cvt_pk_bf16_f32 v32, v40, v41
	ds_read2_b32 v[34:35], v5 offset0:82 offset1:115
	v_ashrrev_i32_e32 v45, 31, v44
	s_waitcnt lgkmcnt(0)
	v_cvt_pk_bf16_f32 v33, v34, v35
	ds_read2_b32 v[34:35], v5 offset0:148 offset1:181
	v_lshlrev_b64 v[44:45], 11, v[44:45]
	s_waitcnt lgkmcnt(0)
	v_cvt_pk_bf16_f32 v34, v34, v35
	ds_read2_b32 v[40:41], v5 offset0:214 offset1:247
	s_waitcnt lgkmcnt(0)
	v_cvt_pk_bf16_f32 v35, v40, v41
	v_lshl_add_u64 v[44:45], v[42:43], 0, v[44:45]
	ds_read2_b32 v[40:41], v5 offset0:24 offset1:57
	global_store_dwordx4 v[44:45], v[32:35], off
	v_or_b32_e32 v44, s0, v36
	v_ashrrev_i32_e32 v45, 31, v44
	s_waitcnt lgkmcnt(0)
	v_cvt_pk_bf16_f32 v32, v40, v41
	ds_read2_b32 v[34:35], v5 offset0:90 offset1:123
	s_waitcnt lgkmcnt(0)
	v_cvt_pk_bf16_f32 v33, v34, v35
	ds_read2_b32 v[34:35], v5 offset0:156 offset1:189
	s_waitcnt lgkmcnt(0)
	v_cvt_pk_bf16_f32 v34, v34, v35
	ds_read2_b32 v[40:41], v5 offset0:222 offset1:255
	v_lshlrev_b64 v[44:45], 11, v[44:45]
	s_waitcnt lgkmcnt(0)
	v_cvt_pk_bf16_f32 v35, v40, v41
	v_lshl_add_u64 v[40:41], v[42:43], 0, v[44:45]
	global_store_dwordx4 v[40:41], v[32:35], off
	s_waitcnt lgkmcnt(0)
	s_branch .LBB0_9

; #pragma unroll 8
;     for (int i = 0; i < 32; ++i) { const int kk = 2 * i + (lane >> 5); scr[kk * 33 + (lane & 31)] = W[(size_t)(k0 + kk) * N + n0 + (lane & 31)]; }
.LBB0_945:
	s_lshl_b32 s11, s5, 1
	s_lshl_b32 s13, s9, 1
	v_or_b32_e32 v54, s11, v1
	v_or_b32_e32 v55, s13, v0
	s_add_i32 s14, s11, 4
	s_add_i32 s15, s13, 4
	s_add_i32 s16, s11, 8
	s_add_i32 s17, s13, 8
	s_add_i32 s18, s11, 12
	s_add_i32 s19, s13, 12
	s_add_i32 s20, s11, 16
	s_add_i32 s21, s13, 16
	s_add_i32 s24, s11, 20
	s_add_i32 s25, s13, 20
	s_add_i32 s26, s11, 24
	s_add_i32 s27, s13, 24
	s_add_i32 s11, s11, 28
	s_add_i32 s13, s13, 28
	v_add_u32_e32 v24, s4, v55
	v_or_b32_e32 v56, s14, v1
	v_or_b32_e32 v57, s15, v0
	v_or_b32_e32 v58, s16, v1
	v_or_b32_e32 v59, s17, v0
	v_or_b32_e32 v60, s18, v1
	v_or_b32_e32 v61, s19, v0
	v_or_b32_e32 v62, s20, v1
	v_or_b32_e32 v63, s21, v0
	v_or_b32_e32 v64, s24, v1
	v_or_b32_e32 v65, s25, v0
	v_or_b32_e32 v66, s26, v1
	v_or_b32_e32 v67, s27, v0
	v_or_b32_e32 v68, s11, v1
	v_or_b32_e32 v69, s13, v0
	v_add_u32_e32 v22, s6, v54
	v_ashrrev_i32_e32 v25, 31, v24
	v_add_u32_e32 v26, s6, v56
	v_add_u32_e32 v28, s4, v57
	v_add_u32_e32 v30, s6, v58
	v_add_u32_e32 v32, s4, v59
	v_add_u32_e32 v34, s6, v60
	v_add_u32_e32 v36, s4, v61
	v_add_u32_e32 v38, s6, v62
	v_add_u32_e32 v40, s4, v63
	v_add_u32_e32 v42, s6, v64
	v_add_u32_e32 v44, s4, v65
	v_add_u32_e32 v46, s6, v66
	v_add_u32_e32 v48, s4, v67
	v_add_u32_e32 v50, s6, v68
	v_add_u32_e32 v52, s4, v69
	v_ashrrev_i32_e32 v23, 31, v22
	v_lshlrev_b64 v[24:25], 12, v[24:25]
	v_ashrrev_i32_e32 v29, 31, v28
	v_ashrrev_i32_e32 v27, 31, v26
	v_ashrrev_i32_e32 v33, 31, v32
	v_ashrrev_i32_e32 v31, 31, v30
	v_ashrrev_i32_e32 v37, 31, v36
	v_ashrrev_i32_e32 v35, 31, v34
	v_ashrrev_i32_e32 v41, 31, v40
	v_ashrrev_i32_e32 v39, 31, v38
	v_ashrrev_i32_e32 v45, 31, v44
	v_ashrrev_i32_e32 v43, 31, v42
	v_ashrrev_i32_e32 v49, 31, v48
	v_ashrrev_i32_e32 v47, 31, v46
	v_ashrrev_i32_e32 v53, 31, v52
	v_ashrrev_i32_e32 v51, 31, v50
	v_lshlrev_b64 v[22:23], 12, v[22:23]
	v_lshl_add_u64 v[24:25], v[16:17], 0, v[24:25]
	v_lshlrev_b64 v[26:27], 12, v[26:27]
	v_lshlrev_b64 v[28:29], 12, v[28:29]
	v_lshlrev_b64 v[30:31], 12, v[30:31]
	v_lshlrev_b64 v[32:33], 12, v[32:33]
	v_lshlrev_b64 v[34:35], 12, v[34:35]
	v_lshlrev_b64 v[36:37], 12, v[36:37]
	v_lshlrev_b64 v[38:39], 12, v[38:39]
	v_lshlrev_b64 v[40:41], 12, v[40:41]
	v_lshlrev_b64 v[42:43], 12, v[42:43]
	v_lshlrev_b64 v[44:45], 12, v[44:45]
	v_lshlrev_b64 v[46:47], 12, v[46:47]
	v_lshlrev_b64 v[48:49], 12, v[48:49]
	v_lshlrev_b64 v[50:51], 12, v[50:51]
	v_lshlrev_b64 v[52:53], 12, v[52:53]
	v_lshl_add_u64 v[22:23], v[16:17], 0, v[22:23]
	v_lshl_add_u64 v[28:29], v[16:17], 0, v[28:29]
	v_lshl_add_u64 v[26:27], v[16:17], 0, v[26:27]
	v_lshl_add_u64 v[32:33], v[16:17], 0, v[32:33]
	v_lshl_add_u64 v[30:31], v[16:17], 0, v[30:31]
	v_lshl_add_u64 v[36:37], v[16:17], 0, v[36:37]
	v_lshl_add_u64 v[34:35], v[16:17], 0, v[34:35]
	v_lshl_add_u64 v[40:41], v[16:17], 0, v[40:41]
	v_lshl_add_u64 v[38:39], v[16:17], 0, v[38:39]
	v_lshl_add_u64 v[44:45], v[16:17], 0, v[44:45]
	v_lshl_add_u64 v[42:43], v[16:17], 0, v[42:43]
	v_lshl_add_u64 v[48:49], v[16:17], 0, v[48:49]
	v_lshl_add_u64 v[46:47], v[16:17], 0, v[46:47]
	v_lshl_add_u64 v[52:53], v[16:17], 0, v[52:53]
	v_lshl_add_u64 v[50:51], v[16:17], 0, v[50:51]
	global_load_dword v70, v[24:25], off nt
	global_load_dword v71, v[22:23], off nt
	global_load_dword v72, v[28:29], off nt
	global_load_dword v73, v[26:27], off nt
	global_load_dword v74, v[32:33], off nt
	global_load_dword v75, v[30:31], off nt
	global_load_dword v76, v[36:37], off nt
	global_load_dword v77, v[34:35], off nt
	global_load_dword v78, v[40:41], off nt
	global_load_dword v79, v[38:39], off nt
	global_load_dword v80, v[44:45], off nt
	global_load_dword v81, v[42:43], off nt
	global_load_dword v82, v[48:49], off nt
	global_load_dword v83, v[46:47], off nt
	global_load_dword v84, v[52:53], off nt
	global_load_dword v85, v[50:51], off nt
	s_add_i32 s9, s9, 16
	s_add_i32 s5, s5, 16
	s_add_i32 s10, s10, -16
	v_mad_u64_u32 v[22:23], s[14:15], v55, s1, v[4:5]
	s_cmp_lg_u32 s10, 0
	v_mad_u64_u32 v[24:25], s[14:15], v54, s1, v[4:5]
	v_mad_u64_u32 v[26:27], s[14:15], v57, s1, v[4:5]
	v_mad_u64_u32 v[28:29], s[14:15], v56, s1, v[4:5]
	v_mad_u64_u32 v[30:31], s[14:15], v59, s1, v[4:5]
	v_mad_u64_u32 v[32:33], s[14:15], v58, s1, v[4:5]
	v_mad_u64_u32 v[34:35], s[14:15], v61, s1, v[4:5]
	v_mad_u64_u32 v[36:37], s[14:15], v60, s1, v[4:5]
	v_mad_u64_u32 v[38:39], s[14:15], v63, s1, v[4:5]
	v_mad_u64_u32 v[40:41], s[14:15], v62, s1, v[4:5]
	v_mad_u64_u32 v[42:43], s[14:15], v65, s1, v[4:5]
	v_mad_u64_u32 v[44:45], s[14:15], v64, s1, v[4:5]
	v_mad_u64_u32 v[46:47], s[14:15], v67, s1, v[4:5]
	v_mad_u64_u32 v[48:49], s[14:15], v66, s1, v[4:5]
	v_mad_u64_u32 v[50:51], s[14:15], v69, s1, v[4:5]
	v_mad_u64_u32 v[52:53], s[14:15], v68, s1, v[4:5]
	s_waitcnt vmcnt(15)
	ds_write_b32 v22, v70
	s_waitcnt vmcnt(14)
	ds_write_b32 v24, v71
	s_waitcnt vmcnt(13)
	ds_write_b32 v26, v72
	s_waitcnt vmcnt(12)
	ds_write_b32 v28, v73
	s_waitcnt vmcnt(11)
	ds_write_b32 v30, v74
	s_waitcnt vmcnt(10)
	ds_write_b32 v32, v75
	s_waitcnt vmcnt(9)
	ds_write_b32 v34, v76
	s_waitcnt vmcnt(8)
	ds_write_b32 v36, v77
	s_waitcnt vmcnt(7)
	ds_write_b32 v38, v78
	s_waitcnt vmcnt(6)
	ds_write_b32 v40, v79
	s_waitcnt vmcnt(5)
	ds_write_b32 v42, v80
	s_waitcnt vmcnt(4)
	ds_write_b32 v44, v81
	s_waitcnt vmcnt(3)
	ds_write_b32 v46, v82
	s_waitcnt vmcnt(2)
	ds_write_b32 v48, v83
	s_waitcnt vmcnt(1)
	ds_write_b32 v50, v84
	s_waitcnt vmcnt(0)
	ds_write_b32 v52, v85
	s_cbranch_scc1 .LBB0_945
; #define LAS __attribute__((address_space(3)))
; __device__ __forceinline__ unsigned pkbf(float lo, float hi) { return pg8::cvt_pk_bf16(lo, hi); }
;     ...
;     asm volatile("s_waitcnt lgkmcnt(0)" ::: "memory");
;     const int c = lane & 7;
; #pragma unroll
;     for (int j = 0; j < 4; ++j) { const int n = (lane >> 3) + 8 * j; const LAS float* s = scr + (8 * c) * 33 + n;
;         u32x4 o; o.x = pkbf(s[0 * 33] * sc, s[1 * 33] * sc); o.y = pkbf(s[2 * 33] * sc, s[3 * 33] * sc); o.z = pkbf(s[4 * 33] * sc, s[5 * 33] * sc); o.w = pkbf(s[6 * 33] * sc, s[7 * 33] * sc);
;         const int dn = ropeperm ? (n < 16 ? 2 * n : 2 * (n - 16) + 1) : n;
;         *(u32x4*)(WT + (size_t)(drow0 + dn) * ldk + kdst0 + k0 + 8 * c) = o; }
;     asm volatile("s_waitcnt lgkmcnt(0)" ::: "memory");
; __device__ __forceinline__ void prologue(const P& p, LAS unsigned char* lds, int gw, int NGW, int wave, int lane, int gtid, int GT, int which) {
;     ...
;         if (r < I_OUT) { const int kb = r / 32, nb = r % 32; transpose_item(p.in[24], DM, kb * 64, nb * 32, (bf16_t*)(ws + WS_WOUT), DM, 0, nb * 32, false, scr, lane); continue; }
	s_waitcnt lgkmcnt(0)
	ds_read2_b32 v[16:17], v18 offset1:33
	s_waitcnt lgkmcnt(0)
	v_cvt_pk_bf16_f32 v22, v16, v17
	ds_read2_b32 v[16:17], v18 offset0:66 offset1:99
	s_waitcnt lgkmcnt(0)
	v_cvt_pk_bf16_f32 v23, v16, v17
	ds_read2_b32 v[16:17], v18 offset0:132 offset1:165
	s_mov_b32 s5, s7
	v_or_b32_e32 v26, s8, v5
	s_waitcnt lgkmcnt(0)
	v_cvt_pk_bf16_f32 v24, v16, v17
	ds_read2_b32 v[16:17], v18 offset0:198 offset1:231
	v_mov_b32_e32 v27, v3
	v_lshl_add_u64 v[28:29], s[4:5], 1, v[6:7]
	v_lshlrev_b32_e32 v26, 11, v26
	s_waitcnt lgkmcnt(0)
	v_cvt_pk_bf16_f32 v25, v16, v17
	ds_read2_b32 v[16:17], v18 offset0:8 offset1:41
	v_lshl_add_u64 v[26:27], v[28:29], 0, v[26:27]
	global_store_dwordx4 v[26:27], v[22:25], off
	v_or_b32_e32 v26, s8, v19
	v_mov_b32_e32 v27, v3
	s_waitcnt lgkmcnt(0)
	v_cvt_pk_bf16_f32 v22, v16, v17
	ds_read2_b32 v[16:17], v18 offset0:74 offset1:107
	s_waitcnt lgkmcnt(0)
	v_cvt_pk_bf16_f32 v23, v16, v17
	ds_read2_b32 v[16:17], v18 offset0:140 offset1:173
	s_waitcnt lgkmcnt(0)
	v_cvt_pk_bf16_f32 v24, v16, v17
	ds_read2_b32 v[16:17], v18 offset0:206 offset1:239
	v_lshlrev_b32_e32 v26, 11, v26
	s_waitcnt lgkmcnt(0)
	v_cvt_pk_bf16_f32 v25, v16, v17
	ds_read2_b32 v[16:17], v18 offset0:16 offset1:49
	v_lshl_add_u64 v[26:27], v[28:29], 0, v[26:27]
	global_store_dwordx4 v[26:27], v[22:25], off
	v_or_b32_e32 v26, s8, v20
	v_mov_b32_e32 v27, v3
	s_waitcnt lgkmcnt(0)
	v_cvt_pk_bf16_f32 v22, v16, v17
	ds_read2_b32 v[16:17], v18 offset0:82 offset1:115
	s_waitcnt lgkmcnt(0)
	v_cvt_pk_bf16_f32 v23, v16, v17
	ds_read2_b32 v[16:17], v18 offset0:148 offset1:181
	s_waitcnt lgkmcnt(0)
	v_cvt_pk_bf16_f32 v24, v16, v17
	ds_read2_b32 v[16:17], v18 offset0:214 offset1:247
	v_lshlrev_b32_e32 v26, 11, v26
	s_waitcnt lgkmcnt(0)
	v_cvt_pk_bf16_f32 v25, v16, v17
	ds_read2_b32 v[16:17], v18 offset0:24 offset1:57
	v_lshl_add_u64 v[26:27], v[28:29], 0, v[26:27]
	global_store_dwordx4 v[26:27], v[22:25], off
	v_mov_b32_e32 v27, v3
	s_waitcnt lgkmcnt(0)
	v_cvt_pk_bf16_f32 v22, v16, v17
	ds_read2_b32 v[16:17], v18 offset0:90 offset1:123
	s_waitcnt lgkmcnt(0)
	v_cvt_pk_bf16_f32 v23, v16, v17
	ds_read2_b32 v[16:17], v18 offset0:156 offset1:189
	v_or_b32_e32 v25, s8, v21
	s_waitcnt lgkmcnt(0)
	v_cvt_pk_bf16_f32 v24, v16, v17
	ds_read2_b32 v[16:17], v18 offset0:222 offset1:255
	v_lshlrev_b32_e32 v26, 11, v25
	s_waitcnt lgkmcnt(0)
	v_cvt_pk_bf16_f32 v25, v16, v17
	v_lshl_add_u64 v[16:17], v[28:29], 0, v[26:27]
	global_store_dwordx4 v[16:17], v[22:25], off
	s_waitcnt lgkmcnt(0)

; #pragma unroll 8
;     for (int i = 0; i < 32; ++i) { const int kk = 2 * i + (lane >> 5); scr[kk * 33 + (lane & 31)] = W[(size_t)(k0 + kk) * N + n0 + (lane & 31)]; }
.LBB0_952:
	s_lshl_b32 s13, s5, 1
	s_lshl_b32 s14, s9, 1
	v_or_b32_e32 v54, s13, v1
	v_or_b32_e32 v55, s14, v0
	s_add_i32 s15, s13, 4
	s_add_i32 s16, s14, 4
	s_add_i32 s17, s13, 8
	s_add_i32 s18, s14, 8
	s_add_i32 s19, s13, 12
	s_add_i32 s20, s14, 12
	s_add_i32 s21, s13, 16
	s_add_i32 s24, s14, 16
	s_add_i32 s25, s13, 20
	s_add_i32 s26, s14, 20
	s_add_i32 s27, s13, 24
	s_add_i32 s28, s14, 24
	s_add_i32 s13, s13, 28
	s_add_i32 s14, s14, 28
	v_add_u32_e32 v24, s4, v55
	v_or_b32_e32 v56, s15, v1
	v_or_b32_e32 v57, s16, v0
	v_or_b32_e32 v58, s17, v1
	v_or_b32_e32 v59, s18, v0
	v_or_b32_e32 v60, s19, v1
	v_or_b32_e32 v61, s20, v0
	v_or_b32_e32 v62, s21, v1
	v_or_b32_e32 v63, s24, v0
	v_or_b32_e32 v64, s25, v1
	v_or_b32_e32 v65, s26, v0
	v_or_b32_e32 v66, s27, v1
	v_or_b32_e32 v67, s28, v0
	v_or_b32_e32 v68, s13, v1
	v_or_b32_e32 v69, s14, v0
	v_add_u32_e32 v22, s6, v54
	v_ashrrev_i32_e32 v25, 31, v24
	v_add_u32_e32 v26, s6, v56
	v_add_u32_e32 v28, s4, v57
	v_add_u32_e32 v30, s6, v58
	v_add_u32_e32 v32, s4, v59
	v_add_u32_e32 v34, s6, v60
	v_add_u32_e32 v36, s4, v61
	v_add_u32_e32 v38, s6, v62
	v_add_u32_e32 v40, s4, v63
	v_add_u32_e32 v42, s6, v64
	v_add_u32_e32 v44, s4, v65
	v_add_u32_e32 v46, s6, v66
	v_add_u32_e32 v48, s4, v67
	v_add_u32_e32 v50, s6, v68
	v_add_u32_e32 v52, s4, v69
	v_ashrrev_i32_e32 v23, 31, v22
	v_lshlrev_b64 v[24:25], 12, v[24:25]
	v_ashrrev_i32_e32 v29, 31, v28
	v_ashrrev_i32_e32 v27, 31, v26
	v_ashrrev_i32_e32 v33, 31, v32
	v_ashrrev_i32_e32 v31, 31, v30
	v_ashrrev_i32_e32 v37, 31, v36
	v_ashrrev_i32_e32 v35, 31, v34
	v_ashrrev_i32_e32 v41, 31, v40
	v_ashrrev_i32_e32 v39, 31, v38
	v_ashrrev_i32_e32 v45, 31, v44
	v_ashrrev_i32_e32 v43, 31, v42
	v_ashrrev_i32_e32 v49, 31, v48
	v_ashrrev_i32_e32 v47, 31, v46
	v_ashrrev_i32_e32 v53, 31, v52
	v_ashrrev_i32_e32 v51, 31, v50
	v_lshlrev_b64 v[22:23], 12, v[22:23]
	v_lshl_add_u64 v[24:25], v[16:17], 0, v[24:25]
	v_lshlrev_b64 v[26:27], 12, v[26:27]
	v_lshlrev_b64 v[28:29], 12, v[28:29]
	v_lshlrev_b64 v[30:31], 12, v[30:31]
	v_lshlrev_b64 v[32:33], 12, v[32:33]
	v_lshlrev_b64 v[34:35], 12, v[34:35]
	v_lshlrev_b64 v[36:37], 12, v[36:37]
	v_lshlrev_b64 v[38:39], 12, v[38:39]
	v_lshlrev_b64 v[40:41], 12, v[40:41]
	v_lshlrev_b64 v[42:43], 12, v[42:43]
	v_lshlrev_b64 v[44:45], 12, v[44:45]
	v_lshlrev_b64 v[46:47], 12, v[46:47]
	v_lshlrev_b64 v[48:49], 12, v[48:49]
	v_lshlrev_b64 v[50:51], 12, v[50:51]
	v_lshlrev_b64 v[52:53], 12, v[52:53]
	v_lshl_add_u64 v[22:23], v[16:17], 0, v[22:23]
	v_lshl_add_u64 v[28:29], v[16:17], 0, v[28:29]
	v_lshl_add_u64 v[26:27], v[16:17], 0, v[26:27]
	v_lshl_add_u64 v[32:33], v[16:17], 0, v[32:33]
	v_lshl_add_u64 v[30:31], v[16:17], 0, v[30:31]
	v_lshl_add_u64 v[36:37], v[16:17], 0, v[36:37]
	v_lshl_add_u64 v[34:35], v[16:17], 0, v[34:35]
	v_lshl_add_u64 v[40:41], v[16:17], 0, v[40:41]
	v_lshl_add_u64 v[38:39], v[16:17], 0, v[38:39]
	v_lshl_add_u64 v[44:45], v[16:17], 0, v[44:45]
	v_lshl_add_u64 v[42:43], v[16:17], 0, v[42:43]
	v_lshl_add_u64 v[48:49], v[16:17], 0, v[48:49]
	v_lshl_add_u64 v[46:47], v[16:17], 0, v[46:47]
	v_lshl_add_u64 v[52:53], v[16:17], 0, v[52:53]
	v_lshl_add_u64 v[50:51], v[16:17], 0, v[50:51]
	global_load_dword v70, v[24:25], off nt
	global_load_dword v71, v[22:23], off nt
	global_load_dword v72, v[28:29], off nt
	global_load_dword v73, v[26:27], off nt
	global_load_dword v74, v[32:33], off nt
	global_load_dword v75, v[30:31], off nt
	global_load_dword v76, v[36:37], off nt
	global_load_dword v77, v[34:35], off nt
	global_load_dword v78, v[40:41], off nt
	global_load_dword v79, v[38:39], off nt
	global_load_dword v80, v[44:45], off nt
	global_load_dword v81, v[42:43], off nt
	global_load_dword v82, v[48:49], off nt
	global_load_dword v83, v[46:47], off nt
	global_load_dword v84, v[52:53], off nt
	global_load_dword v85, v[50:51], off nt
	s_add_i32 s9, s9, 16
	s_add_i32 s5, s5, 16
	s_add_i32 s11, s11, -16
	v_mad_u64_u32 v[22:23], s[14:15], v55, s1, v[4:5]
	s_cmp_lg_u32 s11, 0
	v_mad_u64_u32 v[24:25], s[14:15], v54, s1, v[4:5]
	v_mad_u64_u32 v[26:27], s[14:15], v57, s1, v[4:5]
	v_mad_u64_u32 v[28:29], s[14:15], v56, s1, v[4:5]
	v_mad_u64_u32 v[30:31], s[14:15], v59, s1, v[4:5]
	v_mad_u64_u32 v[32:33], s[14:15], v58, s1, v[4:5]
	v_mad_u64_u32 v[34:35], s[14:15], v61, s1, v[4:5]
	v_mad_u64_u32 v[36:37], s[14:15], v60, s1, v[4:5]
	v_mad_u64_u32 v[38:39], s[14:15], v63, s1, v[4:5]
	v_mad_u64_u32 v[40:41], s[14:15], v62, s1, v[4:5]
	v_mad_u64_u32 v[42:43], s[14:15], v65, s1, v[4:5]
	v_mad_u64_u32 v[44:45], s[14:15], v64, s1, v[4:5]
	v_mad_u64_u32 v[46:47], s[14:15], v67, s1, v[4:5]
	v_mad_u64_u32 v[48:49], s[14:15], v66, s1, v[4:5]
	v_mad_u64_u32 v[50:51], s[14:15], v69, s1, v[4:5]
	v_mad_u64_u32 v[52:53], s[14:15], v68, s1, v[4:5]
	s_waitcnt vmcnt(15)
	ds_write_b32 v22, v70
	s_waitcnt vmcnt(14)
	ds_write_b32 v24, v71
	s_waitcnt vmcnt(13)
	ds_write_b32 v26, v72
	s_waitcnt vmcnt(12)
	ds_write_b32 v28, v73
	s_waitcnt vmcnt(11)
	ds_write_b32 v30, v74
	s_waitcnt vmcnt(10)
	ds_write_b32 v32, v75
	s_waitcnt vmcnt(9)
	ds_write_b32 v34, v76
	s_waitcnt vmcnt(8)
	ds_write_b32 v36, v77
	s_waitcnt vmcnt(7)
	ds_write_b32 v38, v78
	s_waitcnt vmcnt(6)
	ds_write_b32 v40, v79
	s_waitcnt vmcnt(5)
	ds_write_b32 v42, v80
	s_waitcnt vmcnt(4)
	ds_write_b32 v44, v81
	s_waitcnt vmcnt(3)
	ds_write_b32 v46, v82
	s_waitcnt vmcnt(2)
	ds_write_b32 v48, v83
	s_waitcnt vmcnt(1)
	ds_write_b32 v50, v84
	s_waitcnt vmcnt(0)
	ds_write_b32 v52, v85
	s_cbranch_scc1 .LBB0_952
; #define LAS __attribute__((address_space(3)))
; __device__ __forceinline__ unsigned pkbf(float lo, float hi) { return pg8::cvt_pk_bf16(lo, hi); }
;     ...
;     asm volatile("s_waitcnt lgkmcnt(0)" ::: "memory");
;     const int c = lane & 7;
; #pragma unroll
;     for (int j = 0; j < 4; ++j) { const int n = (lane >> 3) + 8 * j; const LAS float* s = scr + (8 * c) * 33 + n;
;         u32x4 o; o.x = pkbf(s[0 * 33] * sc, s[1 * 33] * sc); o.y = pkbf(s[2 * 33] * sc, s[3 * 33] * sc); o.z = pkbf(s[4 * 33] * sc, s[5 * 33] * sc); o.w = pkbf(s[6 * 33] * sc, s[7 * 33] * sc);
;         const int dn = ropeperm ? (n < 16 ? 2 * n : 2 * (n - 16) + 1) : n;
;         *(u32x4*)(WT + (size_t)(drow0 + dn) * ldk + kdst0 + k0 + 8 * c) = o; }
;     asm volatile("s_waitcnt lgkmcnt(0)" ::: "memory");
; __device__ __forceinline__ void prologue(const P& p, LAS unsigned char* lds, int gw, int NGW, int wave, int lane, int gtid, int GT, int which) {
;     ...
;             else { r -= 2 * I_G; const int kb = r / 32, nb = r % 32; transpose_item(wd, DM, kb * 64, nb * 32, WD, DFF, 0, nb * 32, false, scr, lane); }
	s_waitcnt lgkmcnt(0)
	ds_read2_b32 v[16:17], v18 offset1:33
	s_waitcnt lgkmcnt(0)
	v_cvt_pk_bf16_f32 v22, v16, v17
	ds_read2_b32 v[16:17], v18 offset0:66 offset1:99
	v_or_b32_e32 v26, s8, v5
	s_waitcnt lgkmcnt(0)
	v_cvt_pk_bf16_f32 v23, v16, v17
	ds_read2_b32 v[16:17], v18 offset0:132 offset1:165
	s_mov_b32 s5, s7
	v_mul_u32_u24_e32 v26, 0xb00, v26
	s_waitcnt lgkmcnt(0)
	v_cvt_pk_bf16_f32 v24, v16, v17
	ds_read2_b32 v[16:17], v18 offset0:198 offset1:231
	v_mov_b32_e32 v27, v3
	v_lshl_add_u64 v[28:29], s[4:5], 1, v[12:13]
	v_lshlrev_b32_e32 v26, 1, v26
	s_waitcnt lgkmcnt(0)
	v_cvt_pk_bf16_f32 v25, v16, v17
	ds_read2_b32 v[16:17], v18 offset0:8 offset1:41
	v_lshl_add_u64 v[26:27], v[28:29], 0, v[26:27]
	global_store_dwordx4 v[26:27], v[22:25], off
	v_or_b32_e32 v26, s8, v19
	v_mul_u32_u24_e32 v26, 0xb00, v26
	s_waitcnt lgkmcnt(0)
	v_cvt_pk_bf16_f32 v22, v16, v17
	ds_read2_b32 v[16:17], v18 offset0:74 offset1:107
	s_waitcnt lgkmcnt(0)
	v_cvt_pk_bf16_f32 v23, v16, v17
	ds_read2_b32 v[16:17], v18 offset0:140 offset1:173
	s_waitcnt lgkmcnt(0)
	v_cvt_pk_bf16_f32 v24, v16, v17
	ds_read2_b32 v[16:17], v18 offset0:206 offset1:239
	v_mov_b32_e32 v27, v3
	v_lshlrev_b32_e32 v26, 1, v26
	s_waitcnt lgkmcnt(0)
	v_cvt_pk_bf16_f32 v25, v16, v17
	ds_read2_b32 v[16:17], v18 offset0:16 offset1:49
	v_lshl_add_u64 v[26:27], v[28:29], 0, v[26:27]
	global_store_dwordx4 v[26:27], v[22:25], off
	v_or_b32_e32 v26, s8, v20
	v_mul_u32_u24_e32 v26, 0xb00, v26
	s_waitcnt lgkmcnt(0)
	v_cvt_pk_bf16_f32 v22, v16, v17
	ds_read2_b32 v[16:17], v18 offset0:82 offset1:115
	s_waitcnt lgkmcnt(0)
	v_cvt_pk_bf16_f32 v23, v16, v17
	ds_read2_b32 v[16:17], v18 offset0:148 offset1:181
	s_waitcnt lgkmcnt(0)
	v_cvt_pk_bf16_f32 v24, v16, v17
	ds_read2_b32 v[16:17], v18 offset0:214 offset1:247
	v_mov_b32_e32 v27, v3
	v_lshlrev_b32_e32 v26, 1, v26
	s_waitcnt lgkmcnt(0)
	v_cvt_pk_bf16_f32 v25, v16, v17
	ds_read2_b32 v[16:17], v18 offset0:24 offset1:57
	v_lshl_add_u64 v[26:27], v[28:29], 0, v[26:27]
	global_store_dwordx4 v[26:27], v[22:25], off
	v_mov_b32_e32 v27, v3
	s_mov_b64 s[4:5], 0
	s_waitcnt lgkmcnt(0)
	v_cvt_pk_bf16_f32 v22, v16, v17
	ds_read2_b32 v[16:17], v18 offset0:90 offset1:123
	v_or_b32_e32 v25, s8, v21
	s_waitcnt lgkmcnt(0)
	v_cvt_pk_bf16_f32 v23, v16, v17
	ds_read2_b32 v[16:17], v18 offset0:156 offset1:189
	v_mul_u32_u24_e32 v25, 0xb00, v25
	s_waitcnt lgkmcnt(0)
	v_cvt_pk_bf16_f32 v24, v16, v17
	ds_read2_b32 v[16:17], v18 offset0:222 offset1:255
	v_lshlrev_b32_e32 v26, 1, v25
	s_waitcnt lgkmcnt(0)
	v_cvt_pk_bf16_f32 v25, v16, v17
	v_lshl_add_u64 v[16:17], v[28:29], 0, v[26:27]
	global_store_dwordx4 v[16:17], v[22:25], off
	s_waitcnt lgkmcnt(0)

; #pragma unroll 8
;     for (int i = 0; i < 32; ++i) { const int kk = 2 * i + (lane >> 5); scr[kk * 33 + (lane & 31)] = W[(size_t)(k0 + kk) * N + n0 + (lane & 31)]; }
.LBB0_956:
	s_lshl_b32 s15, s11, 1
	s_lshl_b32 s16, s13, 1
	v_or_b32_e32 v54, s15, v1
	v_or_b32_e32 v55, s16, v0
	s_add_i32 s17, s15, 4
	s_add_i32 s18, s16, 4
	s_add_i32 s19, s15, 8
	s_add_i32 s20, s16, 8
	s_add_i32 s21, s15, 12
	s_add_i32 s24, s16, 12
	s_add_i32 s25, s15, 16
	s_add_i32 s26, s16, 16
	s_add_i32 s27, s15, 20
	s_add_i32 s28, s16, 20
	s_add_i32 s29, s15, 24
	s_add_i32 s33, s16, 24
	s_add_i32 s15, s15, 28
	s_add_i32 s16, s16, 28
	v_add_u32_e32 v22, s4, v55
	v_or_b32_e32 v56, s17, v1
	v_or_b32_e32 v57, s18, v0
	v_or_b32_e32 v58, s19, v1
	v_or_b32_e32 v59, s20, v0
	v_or_b32_e32 v60, s21, v1
	v_or_b32_e32 v61, s24, v0
	v_or_b32_e32 v62, s25, v1
	v_or_b32_e32 v63, s26, v0
	v_or_b32_e32 v64, s27, v1
	v_or_b32_e32 v65, s28, v0
	v_or_b32_e32 v66, s29, v1
	v_or_b32_e32 v67, s33, v0
	v_or_b32_e32 v68, s15, v1
	v_or_b32_e32 v69, s16, v0
	v_add_u32_e32 v24, s6, v54
	v_mad_i64_i32 v[22:23], s[16:17], v22, s3, v[16:17]
	v_add_u32_e32 v28, s6, v56
	v_add_u32_e32 v26, s4, v57
	v_add_u32_e32 v32, s6, v58
	v_add_u32_e32 v30, s4, v59
	v_add_u32_e32 v36, s6, v60
	v_add_u32_e32 v34, s4, v61
	v_add_u32_e32 v40, s6, v62
	v_add_u32_e32 v38, s4, v63
	v_add_u32_e32 v44, s6, v64
	v_add_u32_e32 v42, s4, v65
	v_add_u32_e32 v48, s6, v66
	v_add_u32_e32 v46, s4, v67
	v_add_u32_e32 v52, s6, v68
	v_add_u32_e32 v50, s4, v69
	v_mad_i64_i32 v[24:25], s[16:17], v24, s3, v[16:17]
	v_mad_i64_i32 v[26:27], s[16:17], v26, s3, v[16:17]
	v_mad_i64_i32 v[28:29], s[16:17], v28, s3, v[16:17]
	v_mad_i64_i32 v[30:31], s[16:17], v30, s3, v[16:17]
	v_mad_i64_i32 v[32:33], s[16:17], v32, s3, v[16:17]
	v_mad_i64_i32 v[34:35], s[16:17], v34, s3, v[16:17]
	v_mad_i64_i32 v[36:37], s[16:17], v36, s3, v[16:17]
	v_mad_i64_i32 v[38:39], s[16:17], v38, s3, v[16:17]
	v_mad_i64_i32 v[40:41], s[16:17], v40, s3, v[16:17]
	v_mad_i64_i32 v[42:43], s[16:17], v42, s3, v[16:17]
	v_mad_i64_i32 v[44:45], s[16:17], v44, s3, v[16:17]
	v_mad_i64_i32 v[46:47], s[16:17], v46, s3, v[16:17]
	v_mad_i64_i32 v[48:49], s[16:17], v48, s3, v[16:17]
	v_mad_i64_i32 v[50:51], s[16:17], v50, s3, v[16:17]
	v_mad_i64_i32 v[52:53], s[16:17], v52, s3, v[16:17]
	global_load_dword v70, v[22:23], off nt
	global_load_dword v71, v[24:25], off nt
	global_load_dword v72, v[26:27], off nt
	global_load_dword v73, v[28:29], off nt
	global_load_dword v74, v[30:31], off nt
	global_load_dword v75, v[32:33], off nt
	global_load_dword v76, v[34:35], off nt
	global_load_dword v77, v[36:37], off nt
	global_load_dword v78, v[38:39], off nt
	global_load_dword v79, v[40:41], off nt
	global_load_dword v80, v[42:43], off nt
	global_load_dword v81, v[44:45], off nt
	global_load_dword v82, v[46:47], off nt
	global_load_dword v83, v[48:49], off nt
	global_load_dword v84, v[50:51], off nt
	global_load_dword v85, v[52:53], off nt
	s_add_i32 s13, s13, 16
	s_add_i32 s11, s11, 16
	s_add_i32 s14, s14, -16
	v_mad_u64_u32 v[22:23], s[16:17], v55, s1, v[4:5]
	s_cmp_lg_u32 s14, 0
	v_mad_u64_u32 v[24:25], s[16:17], v54, s1, v[4:5]
	v_mad_u64_u32 v[26:27], s[16:17], v57, s1, v[4:5]
	v_mad_u64_u32 v[28:29], s[16:17], v56, s1, v[4:5]
	v_mad_u64_u32 v[30:31], s[16:17], v59, s1, v[4:5]
	v_mad_u64_u32 v[32:33], s[16:17], v58, s1, v[4:5]
	v_mad_u64_u32 v[34:35], s[16:17], v61, s1, v[4:5]
	v_mad_u64_u32 v[36:37], s[16:17], v60, s1, v[4:5]
	v_mad_u64_u32 v[38:39], s[16:17], v63, s1, v[4:5]
	v_mad_u64_u32 v[40:41], s[16:17], v62, s1, v[4:5]
	v_mad_u64_u32 v[42:43], s[16:17], v65, s1, v[4:5]
	v_mad_u64_u32 v[44:45], s[16:17], v64, s1, v[4:5]
	v_mad_u64_u32 v[46:47], s[16:17], v67, s1, v[4:5]
	v_mad_u64_u32 v[48:49], s[16:17], v66, s1, v[4:5]
	v_mad_u64_u32 v[50:51], s[16:17], v69, s1, v[4:5]
	v_mad_u64_u32 v[52:53], s[16:17], v68, s1, v[4:5]
	s_waitcnt vmcnt(15)
	ds_write_b32 v22, v70
	s_waitcnt vmcnt(14)
	ds_write_b32 v24, v71
	s_waitcnt vmcnt(13)
	ds_write_b32 v26, v72
	s_waitcnt vmcnt(12)
	ds_write_b32 v28, v73
	s_waitcnt vmcnt(11)
	ds_write_b32 v30, v74
	s_waitcnt vmcnt(10)
	ds_write_b32 v32, v75
	s_waitcnt vmcnt(9)
	ds_write_b32 v34, v76
	s_waitcnt vmcnt(8)
	ds_write_b32 v36, v77
	s_waitcnt vmcnt(7)
	ds_write_b32 v38, v78
	s_waitcnt vmcnt(6)
	ds_write_b32 v40, v79
	s_waitcnt vmcnt(5)
	ds_write_b32 v42, v80
	s_waitcnt vmcnt(4)
	ds_write_b32 v44, v81
	s_waitcnt vmcnt(3)
	ds_write_b32 v46, v82
	s_waitcnt vmcnt(2)
	ds_write_b32 v48, v83
	s_waitcnt vmcnt(1)
	ds_write_b32 v50, v84
	s_waitcnt vmcnt(0)
	ds_write_b32 v52, v85
	s_cbranch_scc1 .LBB0_956
; #define LAS __attribute__((address_space(3)))
; __device__ __forceinline__ unsigned pkbf(float lo, float hi) { return pg8::cvt_pk_bf16(lo, hi); }
;     ...
;     asm volatile("s_waitcnt lgkmcnt(0)" ::: "memory");
;     const int c = lane & 7;
; #pragma unroll
;     for (int j = 0; j < 4; ++j) { const int n = (lane >> 3) + 8 * j; const LAS float* s = scr + (8 * c) * 33 + n;
;         u32x4 o; o.x = pkbf(s[0 * 33] * sc, s[1 * 33] * sc); o.y = pkbf(s[2 * 33] * sc, s[3 * 33] * sc); o.z = pkbf(s[4 * 33] * sc, s[5 * 33] * sc); o.w = pkbf(s[6 * 33] * sc, s[7 * 33] * sc);
;         const int dn = ropeperm ? (n < 16 ? 2 * n : 2 * (n - 16) + 1) : n;
;         *(u32x4*)(WT + (size_t)(drow0 + dn) * ldk + kdst0 + k0 + 8 * c) = o; }
;     asm volatile("s_waitcnt lgkmcnt(0)" ::: "memory");
; __device__ __forceinline__ void prologue(const P& p, LAS unsigned char* lds, int gw, int NGW, int wave, int lane, int gtid, int GT, int which) {
;     ...
;             bf16_t* WGU = (bf16_t*)(ws + (f ? WS_WGU2 : WS_WGU1)); bf16_t* WD = (bf16_t*)(ws + (f ? WS_WD2 : WS_WD1));
;             const float* wg = p.in[f ? 26 : 3]; const float* wu = p.in[f ? 27 : 4]; const float* wd = p.in[f ? 28 : 5];
;             if (r < 2 * I_G) { const bool up = r >= I_G; const int q = up ? r - I_G : r; const int kb = q / 88, nb = q % 88, n0 = nb * 32;
;                 transpose_item(up ? wu : wg, DFF, kb * 64, n0, WGU, DM, 0, (n0 >> 7) * 256 + (n0 & 127) + (up ? 128 : 0), false, scr, lane); }
	s_lshl_b32 s5, s5, 6
	s_and_b64 s[8:9], s[8:9], exec
	s_cselect_b32 s6, 0x80, 0
	s_and_b32 s8, s10, 0x60
	s_waitcnt lgkmcnt(0)
	s_and_b32 s9, s5, 0xffffff00
	s_ashr_i32 s5, s4, 31
	s_or_b32 s6, s8, s6
	ds_read2_b32 v[16:17], v18 offset1:33
	v_lshl_add_u64 v[26:27], s[4:5], 1, v[14:15]
	s_or_b32 s4, s6, s9
	s_waitcnt lgkmcnt(0)
	v_cvt_pk_bf16_f32 v22, v16, v17
	ds_read2_b32 v[16:17], v18 offset0:66 offset1:99
	v_or_b32_e32 v28, s4, v5
	s_waitcnt lgkmcnt(0)
	v_cvt_pk_bf16_f32 v23, v16, v17
	ds_read2_b32 v[16:17], v18 offset0:132 offset1:165
	v_ashrrev_i32_e32 v29, 31, v28
	s_waitcnt lgkmcnt(0)
	v_cvt_pk_bf16_f32 v24, v16, v17
	ds_read2_b32 v[16:17], v18 offset0:198 offset1:231
	v_lshlrev_b64 v[28:29], 11, v[28:29]
	s_waitcnt lgkmcnt(0)
	v_cvt_pk_bf16_f32 v25, v16, v17
	ds_read2_b32 v[16:17], v18 offset0:8 offset1:41
	v_lshl_add_u64 v[28:29], v[26:27], 0, v[28:29]
	global_store_dwordx4 v[28:29], v[22:25], off
	v_or_b32_e32 v28, s4, v19
	v_ashrrev_i32_e32 v29, 31, v28
	s_waitcnt lgkmcnt(0)
	v_cvt_pk_bf16_f32 v22, v16, v17
	ds_read2_b32 v[16:17], v18 offset0:74 offset1:107
	s_waitcnt lgkmcnt(0)
	v_cvt_pk_bf16_f32 v23, v16, v17
	ds_read2_b32 v[16:17], v18 offset0:140 offset1:173
	s_waitcnt lgkmcnt(0)
	v_cvt_pk_bf16_f32 v24, v16, v17
	ds_read2_b32 v[16:17], v18 offset0:206 offset1:239
	v_lshlrev_b64 v[28:29], 11, v[28:29]
	s_waitcnt lgkmcnt(0)
	v_cvt_pk_bf16_f32 v25, v16, v17
	ds_read2_b32 v[16:17], v18 offset0:16 offset1:49
	v_lshl_add_u64 v[28:29], v[26:27], 0, v[28:29]
	global_store_dwordx4 v[28:29], v[22:25], off
	v_or_b32_e32 v28, s4, v20
	v_ashrrev_i32_e32 v29, 31, v28
	s_waitcnt lgkmcnt(0)
	v_cvt_pk_bf16_f32 v22, v16, v17
	ds_read2_b32 v[16:17], v18 offset0:82 offset1:115
	s_waitcnt lgkmcnt(0)
	v_cvt_pk_bf16_f32 v23, v16, v17
	ds_read2_b32 v[16:17], v18 offset0:148 offset1:181
	s_waitcnt lgkmcnt(0)
	v_cvt_pk_bf16_f32 v24, v16, v17
	ds_read2_b32 v[16:17], v18 offset0:214 offset1:247
	v_lshlrev_b64 v[28:29], 11, v[28:29]
	s_waitcnt lgkmcnt(0)
	v_cvt_pk_bf16_f32 v25, v16, v17
	ds_read2_b32 v[16:17], v18 offset0:24 offset1:57
	v_lshl_add_u64 v[28:29], v[26:27], 0, v[28:29]
	global_store_dwordx4 v[28:29], v[22:25], off
	v_or_b32_e32 v28, s4, v21
	v_ashrrev_i32_e32 v29, 31, v28
	s_waitcnt lgkmcnt(0)
	v_cvt_pk_bf16_f32 v22, v16, v17
	ds_read2_b32 v[16:17], v18 offset0:90 offset1:123
	s_waitcnt lgkmcnt(0)
	v_cvt_pk_bf16_f32 v23, v16, v17
	ds_read2_b32 v[16:17], v18 offset0:156 offset1:189
	s_waitcnt lgkmcnt(0)
	v_cvt_pk_bf16_f32 v24, v16, v17
	ds_read2_b32 v[16:17], v18 offset0:222 offset1:255
	v_lshlrev_b64 v[28:29], 11, v[28:29]
	s_waitcnt lgkmcnt(0)
	v_cvt_pk_bf16_f32 v25, v16, v17
	v_lshl_add_u64 v[16:17], v[26:27], 0, v[28:29]
	global_store_dwordx4 v[16:17], v[22:25], off
	s_waitcnt lgkmcnt(0)
	s_branch .LBB0_941

; __device__ __forceinline__ unsigned pkbf(float lo, float hi) { return pg8::cvt_pk_bf16(lo, hi); }
; __device__ __forceinline__ void unpack8bf(const u32x4 w, float* f) { f[0] = bflo(w.x); f[1] = bfhi(w.x); f[2] = bflo(w.y); f[3] = bfhi(w.y); f[4] = bflo(w.z); f[5] = bfhi(w.z); f[6] = bflo(w.w); f[7] = bfhi(w.w); }
; __device__ __forceinline__ void norm_row_bf(const bf16_t* src, const float* gain, bf16_t* ob, float* of, int lane) {
;     float v[16]; float s = 0.f;
;     const u32x4 w0 = *((const u32x4*)src + lane), w1 = *((const u32x4*)src + lane + 64);
;     unpack8bf(w0, v); unpack8bf(w1, v + 8);
; #pragma unroll
;     for (int e = 0; e < 16; ++e) s += v[e] * v[e];
;     const float rstd = 1.0f / sqrtf(wave_sum(s) * (1.f / DM) + NORM_EPS);
; #pragma unroll
;     for (int h = 0; h < 2; ++h) { const float* g = gain + h * 512 + lane * 8; const f32x4 g0 = *(const f32x4*)g, g1 = *(const f32x4*)(g + 4);
;         float o[8];
; #pragma unroll
;         for (int e = 0; e < 4; ++e) { o[e] = v[h * 8 + e] * rstd * g0[e]; o[4 + e] = v[h * 8 + 4 + e] * rstd * g1[e]; }
;         if (ob) { u32x4 w; w.x = pkbf(o[0], o[1]); w.y = pkbf(o[2], o[3]); w.z = pkbf(o[4], o[5]); w.w = pkbf(o[6], o[7]); *((u32x4*)ob + lane + 64 * h) = w; }
;         else { const f32x4 a = {o[0], o[1], o[2], o[3]}, b = {o[4], o[5], o[6], o[7]}; *(f32x4*)(of + h * 512 + lane * 8) = a; *(f32x4*)(of + h * 512 + lane * 8 + 4) = b; } }
; }
.LBB0_1501:
	global_load_dwordx4 v[14:17], v[2:3], off nt
	global_load_dwordx4 v[18:21], v[2:3], off offset:1024 nt
	global_load_dwordx4 v[22:25], v[0:1], off offset:16
	global_load_dwordx4 v[26:29], v[0:1], off
	s_add_i32 s34, s34, s88
	v_lshl_add_u64 v[2:3], v[2:3], 0, s[2:3]
	s_cmp_gt_i32 s34, 0xbfff
	s_waitcnt vmcnt(3)
	v_lshlrev_b32_e32 v34, 16, v14
	v_and_b32_e32 v35, 0xffff0000, v14
	v_lshlrev_b32_e32 v14, 16, v15
	v_and_b32_e32 v15, 0xffff0000, v15
	v_pk_mul_f32 v[44:45], v[34:35], v[34:35]
	v_pk_mul_f32 v[46:47], v[14:15], v[14:15]
	v_add_f32_e32 v44, v44, v45
	v_lshlrev_b32_e32 v32, 16, v16
	v_and_b32_e32 v33, 0xffff0000, v16
	v_add_f32_e32 v44, v46, v44
	s_waitcnt vmcnt(2)
	v_and_b32_e32 v30, 0xffff0000, v21
	v_lshlrev_b32_e32 v31, 16, v21
	v_lshlrev_b32_e32 v36, 16, v20
	v_and_b32_e32 v37, 0xffff0000, v20
	v_pk_mul_f32 v[20:21], v[32:33], v[32:33]
	v_add_f32_e32 v44, v47, v44
	v_lshlrev_b32_e32 v16, 16, v17
	v_and_b32_e32 v17, 0xffff0000, v17
	v_add_f32_e32 v20, v20, v44
	v_pk_mul_f32 v[42:43], v[16:17], v[16:17]
	v_add_f32_e32 v20, v21, v20
	v_lshlrev_b32_e32 v38, 16, v18
	v_and_b32_e32 v39, 0xffff0000, v18
	v_add_f32_e32 v20, v42, v20
	v_pk_mul_f32 v[50:51], v[38:39], v[38:39]
	v_add_f32_e32 v20, v43, v20
	v_lshlrev_b32_e32 v40, 16, v19
	v_and_b32_e32 v41, 0xffff0000, v19
	v_add_f32_e32 v20, v50, v20
	v_pk_mul_f32 v[52:53], v[40:41], v[40:41]
	v_add_f32_e32 v20, v51, v20
	v_add_f32_e32 v20, v52, v20
	v_pk_mul_f32 v[48:49], v[36:37], v[36:37]
	v_add_f32_e32 v20, v53, v20
	v_add_f32_e32 v20, v48, v20
	v_pk_mul_f32 v[18:19], v[30:31], v[30:31]
	v_add_f32_e32 v20, v49, v20
	v_add_f32_e32 v19, v19, v20
	v_add_f32_e32 v18, v18, v19
	ds_bpermute_b32 v19, v6, v18
	s_waitcnt lgkmcnt(0)
	v_add_f32_e32 v18, v18, v19
	ds_bpermute_b32 v19, v7, v18
	s_waitcnt lgkmcnt(0)
	v_add_f32_e32 v18, v18, v19
	ds_bpermute_b32 v19, v8, v18
	s_waitcnt lgkmcnt(0)
	v_add_f32_e32 v18, v18, v19
	ds_bpermute_b32 v19, v9, v18
	s_waitcnt lgkmcnt(0)
	v_add_f32_e32 v18, v18, v19
	ds_bpermute_b32 v19, v10, v18
	s_waitcnt lgkmcnt(0)
	v_add_f32_e32 v18, v18, v19
	ds_bpermute_b32 v19, v11, v18
	s_waitcnt lgkmcnt(0)
	v_add_f32_e32 v18, v18, v19
	v_fmamk_f32 v18, v18, 0x3a800000, v12
	v_mul_f32_e32 v19, 0x4f800000, v18
	v_cmp_gt_f32_e32 vcc, s6, v18
	s_nop 1
	v_cndmask_b32_e32 v18, v18, v19, vcc
	v_sqrt_f32_e32 v19, v18
	s_nop 0
	v_add_u32_e32 v20, -1, v19
	v_add_u32_e32 v21, 1, v19
	v_fma_f32 v42, -v20, v19, v18
	v_fma_f32 v43, -v21, v19, v18
	v_cmp_ge_f32_e64 s[0:1], 0, v42
	s_nop 1
	v_cndmask_b32_e64 v19, v19, v20, s[0:1]
	v_cmp_lt_f32_e64 s[0:1], 0, v43
	s_nop 1
	v_cndmask_b32_e64 v19, v19, v21, s[0:1]
	v_mul_f32_e32 v20, 0x37800000, v19
	v_cndmask_b32_e32 v19, v19, v20, vcc
	v_cmp_class_f32_e32 vcc, v18, v13
	s_nop 1
	v_cndmask_b32_e32 v18, v19, v18, vcc
	v_div_scale_f32 v19, s[0:1], v18, v18, 1.0
	v_rcp_f32_e32 v21, v19
	v_div_scale_f32 v20, vcc, 1.0, v18, 1.0
	v_fma_f32 v42, -v19, v21, 1.0
	v_fmac_f32_e32 v21, v42, v21
	v_mul_f32_e32 v42, v20, v21
	v_fma_f32 v43, -v19, v42, v20
	v_fmac_f32_e32 v42, v43, v21
	v_fma_f32 v19, -v19, v42, v20
	v_div_fmas_f32 v19, v19, v21, v42
	v_div_fixup_f32 v42, v19, v18, 1.0
	v_pk_mul_f32 v[18:19], v[42:43], v[34:35] op_sel_hi:[0,1]
	v_pk_mul_f32 v[14:15], v[42:43], v[14:15] op_sel_hi:[0,1]
	v_pk_mul_f32 v[32:33], v[42:43], v[32:33] op_sel_hi:[0,1]
	v_pk_mul_f32 v[20:21], v[42:43], v[16:17] op_sel_hi:[0,1]
	s_waitcnt vmcnt(0)
	v_pk_mul_f32 v[16:17], v[28:29], v[14:15]
	v_pk_mul_f32 v[14:15], v[26:27], v[18:19]
	v_pk_mul_f32 v[20:21], v[24:25], v[20:21]
	v_pk_mul_f32 v[18:19], v[22:23], v[32:33]
	global_store_dwordx4 v[4:5], v[14:17], off nt
	global_store_dwordx4 v[4:5], v[18:21], off offset:16 nt
	global_load_dwordx4 v[14:17], v[0:1], off offset:2048
	s_nop 0
	global_load_dwordx4 v[18:21], v[0:1], off offset:2064
	v_pk_mul_f32 v[26:27], v[42:43], v[40:41] op_sel_hi:[0,1]
	v_pk_mul_f32 v[28:29], v[42:43], v[38:39] op_sel_hi:[0,1]
	v_pk_mul_f32 v[22:23], v[42:43], v[36:37] op_sel_hi:[0,1]
	v_pk_mul_f32 v[24:25], v[42:43], v[30:31] op_sel_hi:[0,1]
	s_waitcnt vmcnt(1)
	v_pk_mul_f32 v[14:15], v[14:15], v[28:29]
	v_pk_mul_f32 v[16:17], v[16:17], v[26:27]
	s_waitcnt vmcnt(0)
	v_pk_mul_f32 v[18:19], v[18:19], v[22:23]
	v_pk_mul_f32 v[20:21], v[20:21], v[24:25] op_sel:[0,1] op_sel_hi:[1,0]
	global_store_dwordx4 v[4:5], v[14:17], off offset:2048 nt
	global_store_dwordx4 v[4:5], v[18:21], off offset:2064 nt
	v_lshl_add_u64 v[4:5], v[4:5], 0, s[4:5]
	s_cbranch_scc0 .LBB0_1501
